# v9 + remaining loader address adds carried as two SGPR snapshots (all loader LDS-DMA in SGPR-base form, no VALU address math in K-loops)
# speedup vs baseline: 1.0063x; 1.0043x over previous
.LBB0_295:
	ds_read_b128 v[146:149], v155
	ds_read_b128 v[160:163], v155 offset:1024
	ds_read_b128 v[164:167], v155 offset:2048
	ds_read_b128 v[168:171], v155 offset:3072
	ds_read_b128 v[172:175], v156
	ds_read_b128 v[176:179], v156 offset:1024
	ds_read_b128 v[180:183], v156 offset:2048
	ds_read_b128 v[184:187], v156 offset:3072
	s_add_u32 s23, s64, 0xfffc0080
	s_addc_u32 s33, s65, -1
	s_cmp_eq_u32 s92, 12
	s_cselect_b32 s73, s20, s33
	s_cselect_b32 s72, s21, s23
	s_cselect_b32 s71, s19, s91
	s_cselect_b32 s70, s55, s90
	s_add_i32 m0, s76, 0xc000
	ds_read_b128 v[188:191], v157
	ds_read_b128 v[192:195], v157 offset:1024
	ds_read_b128 v[196:199], v157 offset:2048
	ds_read_b128 v[200:203], v157 offset:3072
	ds_read_b128 v[204:207], v157 offset:4096
	ds_read_b128 v[208:211], v157 offset:5120
	ds_read_b128 v[212:215], v157 offset:6144
	ds_read_b128 v[216:219], v157 offset:7168
	global_load_lds_dwordx4 v138, s[64:65]
	s_add_i32 m0, s76, 0xe000
	s_nop 0
	global_load_lds_dwordx4 v140, s[64:65]
	s_waitcnt vmcnt(8)
	s_waitcnt lgkmcnt(0)
	s_barrier
	s_setprio 1
	v_mfma_f32_16x16x32_bf16 v[124:127], v[146:149], v[188:191], v[124:127]
	v_mfma_f32_16x16x32_bf16 v[120:123], v[164:167], v[188:191], v[120:123]
	v_mfma_f32_16x16x32_bf16 v[108:111], v[146:149], v[196:199], v[108:111]
	v_mfma_f32_16x16x32_bf16 v[104:107], v[164:167], v[196:199], v[104:107]
	v_mfma_f32_16x16x32_bf16 v[92:95], v[146:149], v[204:207], v[92:95]
	v_mfma_f32_16x16x32_bf16 v[88:91], v[164:167], v[204:207], v[88:91]
	v_mfma_f32_16x16x32_bf16 v[76:79], v[146:149], v[212:215], v[76:79]
	v_mfma_f32_16x16x32_bf16 v[72:75], v[164:167], v[212:215], v[72:75]
	v_mfma_f32_16x16x32_bf16 v[124:127], v[160:163], v[192:195], v[124:127]
	v_mfma_f32_16x16x32_bf16 v[120:123], v[168:171], v[192:195], v[120:123]
	v_mfma_f32_16x16x32_bf16 v[108:111], v[160:163], v[200:203], v[108:111]
	v_mfma_f32_16x16x32_bf16 v[104:107], v[168:171], v[200:203], v[104:107]
	v_mfma_f32_16x16x32_bf16 v[92:95], v[160:163], v[208:211], v[92:95]
	v_mfma_f32_16x16x32_bf16 v[88:91], v[168:171], v[208:211], v[88:91]
	v_mfma_f32_16x16x32_bf16 v[76:79], v[160:163], v[216:219], v[76:79]
	v_mfma_f32_16x16x32_bf16 v[72:75], v[168:171], v[216:219], v[72:75]
	v_mfma_f32_16x16x32_bf16 v[116:119], v[172:175], v[188:191], v[116:119]
	v_mfma_f32_16x16x32_bf16 v[112:115], v[180:183], v[188:191], v[112:115]
	v_mfma_f32_16x16x32_bf16 v[100:103], v[172:175], v[196:199], v[100:103]
	v_mfma_f32_16x16x32_bf16 v[96:99], v[180:183], v[196:199], v[96:99]
	v_mfma_f32_16x16x32_bf16 v[84:87], v[172:175], v[204:207], v[84:87]
	v_mfma_f32_16x16x32_bf16 v[80:83], v[180:183], v[204:207], v[80:83]
	v_mfma_f32_16x16x32_bf16 v[68:71], v[172:175], v[212:215], v[68:71]
	v_mfma_f32_16x16x32_bf16 v[64:67], v[180:183], v[212:215], v[64:67]
	v_mfma_f32_16x16x32_bf16 v[116:119], v[176:179], v[192:195], v[116:119]
	v_mfma_f32_16x16x32_bf16 v[112:115], v[184:187], v[192:195], v[112:115]
	v_mfma_f32_16x16x32_bf16 v[100:103], v[176:179], v[200:203], v[100:103]
	v_mfma_f32_16x16x32_bf16 v[96:99], v[184:187], v[200:203], v[96:99]
	v_mfma_f32_16x16x32_bf16 v[84:87], v[176:179], v[208:211], v[84:87]
	v_mfma_f32_16x16x32_bf16 v[80:83], v[184:187], v[208:211], v[80:83]
	v_mfma_f32_16x16x32_bf16 v[68:71], v[176:179], v[216:219], v[68:71]
	v_mfma_f32_16x16x32_bf16 v[64:67], v[184:187], v[216:219], v[64:67]
	s_setprio 0
	s_barrier
	s_add_u32 s98, s70, s10
	s_addc_u32 s99, s71, s11
	s_add_u32 s100, s72, s10
	s_addc_u32 s101, s73, s11
	s_add_i32 s23, s85, s74
	s_mov_b32 m0, s23
	ds_read_b128 v[188:191], v157 offset:16384
	ds_read_b128 v[192:195], v157 offset:17408
	ds_read_b128 v[196:199], v157 offset:18432
	ds_read_b128 v[200:203], v157 offset:19456
	ds_read_b128 v[204:207], v157 offset:20480
	ds_read_b128 v[208:211], v157 offset:21504
	ds_read_b128 v[212:215], v157 offset:22528
	ds_read_b128 v[216:219], v157 offset:23552
	global_load_lds_dwordx4 v132, s[70:71]
	s_add_i32 m0, s23, 0x2000
	s_add_u32 s94, s70, 0x40000
	s_addc_u32 s95, s71, 0
	s_add_i32 s23, s86, s74
	global_load_lds_dwordx4 v136, s[70:71]
	s_mov_b32 m0, s23
	s_nop 0
	global_load_lds_dwordx4 v132, s[94:95]
	s_add_i32 m0, s23, 0x2000
	s_nop 0
	global_load_lds_dwordx4 v136, s[94:95]
	s_mov_b32 m0, s76
	s_nop 0
	global_load_lds_dwordx4 v130, s[72:73]
	s_mov_b32 m0, s77
	s_nop 0
	global_load_lds_dwordx4 v134, s[72:73]
	s_waitcnt vmcnt(8)
	s_waitcnt lgkmcnt(0)
	s_barrier
	s_setprio 1
	v_mfma_f32_16x16x32_bf16 v[60:63], v[146:149], v[188:191], v[60:63]
	v_mfma_f32_16x16x32_bf16 v[56:59], v[164:167], v[188:191], v[56:59]
	v_mfma_f32_16x16x32_bf16 v[44:47], v[146:149], v[196:199], v[44:47]
	v_mfma_f32_16x16x32_bf16 v[40:43], v[164:167], v[196:199], v[40:43]
	v_mfma_f32_16x16x32_bf16 v[28:31], v[146:149], v[204:207], v[28:31]
	v_mfma_f32_16x16x32_bf16 v[24:27], v[164:167], v[204:207], v[24:27]
	v_mfma_f32_16x16x32_bf16 v[12:15], v[146:149], v[212:215], v[12:15]
	v_mfma_f32_16x16x32_bf16 v[8:11], v[164:167], v[212:215], v[8:11]
	v_mfma_f32_16x16x32_bf16 v[60:63], v[160:163], v[192:195], v[60:63]
	v_mfma_f32_16x16x32_bf16 v[56:59], v[168:171], v[192:195], v[56:59]
	v_mfma_f32_16x16x32_bf16 v[44:47], v[160:163], v[200:203], v[44:47]
	v_mfma_f32_16x16x32_bf16 v[40:43], v[168:171], v[200:203], v[40:43]
	v_mfma_f32_16x16x32_bf16 v[28:31], v[160:163], v[208:211], v[28:31]
	v_mfma_f32_16x16x32_bf16 v[24:27], v[168:171], v[208:211], v[24:27]
	v_mfma_f32_16x16x32_bf16 v[12:15], v[160:163], v[216:219], v[12:15]
	v_mfma_f32_16x16x32_bf16 v[8:11], v[168:171], v[216:219], v[8:11]
	v_mfma_f32_16x16x32_bf16 v[52:55], v[172:175], v[188:191], v[52:55]
	v_mfma_f32_16x16x32_bf16 v[48:51], v[180:183], v[188:191], v[48:51]
	v_mfma_f32_16x16x32_bf16 v[36:39], v[172:175], v[196:199], v[36:39]
	v_mfma_f32_16x16x32_bf16 v[32:35], v[180:183], v[196:199], v[32:35]
	v_mfma_f32_16x16x32_bf16 v[20:23], v[172:175], v[204:207], v[20:23]
	v_mfma_f32_16x16x32_bf16 v[16:19], v[180:183], v[204:207], v[16:19]
	v_mfma_f32_16x16x32_bf16 v[4:7], v[172:175], v[212:215], v[4:7]
	v_mfma_f32_16x16x32_bf16 v[0:3], v[180:183], v[212:215], v[0:3]
	v_mfma_f32_16x16x32_bf16 v[52:55], v[176:179], v[192:195], v[52:55]
	v_mfma_f32_16x16x32_bf16 v[48:51], v[184:187], v[192:195], v[48:51]
	v_mfma_f32_16x16x32_bf16 v[36:39], v[176:179], v[200:203], v[36:39]
	v_mfma_f32_16x16x32_bf16 v[32:35], v[184:187], v[200:203], v[32:35]
	v_mfma_f32_16x16x32_bf16 v[20:23], v[176:179], v[208:211], v[20:23]
	v_mfma_f32_16x16x32_bf16 v[16:19], v[184:187], v[208:211], v[16:19]
	v_mfma_f32_16x16x32_bf16 v[4:7], v[176:179], v[216:219], v[4:7]
	v_mfma_f32_16x16x32_bf16 v[0:3], v[184:187], v[216:219], v[0:3]
	s_setprio 0
	s_barrier
	s_add_i32 s23, 0, 0x18000
	v_add_u32_e32 v159, s23, v153
	s_add_i32 s33, 0, 0x1c000
	ds_read_b128 v[146:149], v159
	ds_read_b128 v[160:163], v159 offset:1024
	ds_read_b128 v[164:167], v159 offset:2048
	ds_read_b128 v[168:171], v159 offset:3072
	v_add_u32_e32 v159, s33, v153
	ds_read_b128 v[172:175], v159
	ds_read_b128 v[176:179], v159 offset:1024
	ds_read_b128 v[180:183], v159 offset:2048
	ds_read_b128 v[184:187], v159 offset:3072
	s_add_u32 s72, s72, 0x40000
	s_addc_u32 s73, s73, 0
	s_mov_b32 m0, s78
	ds_read_b128 v[188:191], v157 offset:32768
	ds_read_b128 v[192:195], v157 offset:33792
	ds_read_b128 v[196:199], v157 offset:34816
	ds_read_b128 v[200:203], v157 offset:35840
	ds_read_b128 v[204:207], v157 offset:36864
	ds_read_b128 v[208:211], v157 offset:37888
	ds_read_b128 v[212:215], v157 offset:38912
	ds_read_b128 v[216:219], v157 offset:39936
	global_load_lds_dwordx4 v130, s[72:73]
	s_mov_b32 m0, s79
	s_nop 0
	global_load_lds_dwordx4 v134, s[72:73]
	s_waitcnt vmcnt(8)
	s_waitcnt lgkmcnt(0)
	s_barrier
	s_setprio 1
	v_mfma_f32_16x16x32_bf16 v[124:127], v[146:149], v[188:191], v[124:127]
	v_mfma_f32_16x16x32_bf16 v[120:123], v[164:167], v[188:191], v[120:123]
	v_mfma_f32_16x16x32_bf16 v[108:111], v[146:149], v[196:199], v[108:111]
	v_mfma_f32_16x16x32_bf16 v[104:107], v[164:167], v[196:199], v[104:107]
	v_mfma_f32_16x16x32_bf16 v[92:95], v[146:149], v[204:207], v[92:95]
	v_mfma_f32_16x16x32_bf16 v[88:91], v[164:167], v[204:207], v[88:91]
	v_mfma_f32_16x16x32_bf16 v[76:79], v[146:149], v[212:215], v[76:79]
	v_mfma_f32_16x16x32_bf16 v[72:75], v[164:167], v[212:215], v[72:75]
	v_mfma_f32_16x16x32_bf16 v[124:127], v[160:163], v[192:195], v[124:127]
	v_mfma_f32_16x16x32_bf16 v[120:123], v[168:171], v[192:195], v[120:123]
	v_mfma_f32_16x16x32_bf16 v[108:111], v[160:163], v[200:203], v[108:111]
	v_mfma_f32_16x16x32_bf16 v[104:107], v[168:171], v[200:203], v[104:107]
	v_mfma_f32_16x16x32_bf16 v[92:95], v[160:163], v[208:211], v[92:95]
	v_mfma_f32_16x16x32_bf16 v[88:91], v[168:171], v[208:211], v[88:91]
	v_mfma_f32_16x16x32_bf16 v[76:79], v[160:163], v[216:219], v[76:79]
	v_mfma_f32_16x16x32_bf16 v[72:75], v[168:171], v[216:219], v[72:75]
	v_mfma_f32_16x16x32_bf16 v[116:119], v[172:175], v[188:191], v[116:119]
	v_mfma_f32_16x16x32_bf16 v[112:115], v[180:183], v[188:191], v[112:115]
	v_mfma_f32_16x16x32_bf16 v[100:103], v[172:175], v[196:199], v[100:103]
	v_mfma_f32_16x16x32_bf16 v[96:99], v[180:183], v[196:199], v[96:99]
	v_mfma_f32_16x16x32_bf16 v[84:87], v[172:175], v[204:207], v[84:87]
	v_mfma_f32_16x16x32_bf16 v[80:83], v[180:183], v[204:207], v[80:83]
	v_mfma_f32_16x16x32_bf16 v[68:71], v[172:175], v[212:215], v[68:71]
	v_mfma_f32_16x16x32_bf16 v[64:67], v[180:183], v[212:215], v[64:67]
	v_mfma_f32_16x16x32_bf16 v[116:119], v[176:179], v[192:195], v[116:119]
	v_mfma_f32_16x16x32_bf16 v[112:115], v[184:187], v[192:195], v[112:115]
	v_mfma_f32_16x16x32_bf16 v[100:103], v[176:179], v[200:203], v[100:103]
	v_mfma_f32_16x16x32_bf16 v[96:99], v[184:187], v[200:203], v[96:99]
	v_mfma_f32_16x16x32_bf16 v[84:87], v[176:179], v[208:211], v[84:87]
	v_mfma_f32_16x16x32_bf16 v[80:83], v[184:187], v[208:211], v[80:83]
	v_mfma_f32_16x16x32_bf16 v[68:71], v[176:179], v[216:219], v[68:71]
	v_mfma_f32_16x16x32_bf16 v[64:67], v[184:187], v[216:219], v[64:67]
	s_setprio 0
	s_barrier
	s_add_i32 s23, s23, s74
	s_mov_b32 m0, s23
	ds_read_b128 v[188:191], v157 offset:49152
	ds_read_b128 v[192:195], v157 offset:50176
	ds_read_b128 v[196:199], v157 offset:51200
	ds_read_b128 v[200:203], v157 offset:52224
	ds_read_b128 v[204:207], v157 offset:53248
	ds_read_b128 v[208:211], v157 offset:54272
	ds_read_b128 v[212:215], v157 offset:55296
	ds_read_b128 v[216:219], v157 offset:56320
	global_load_lds_dwordx4 v132, s[98:99]
	s_add_i32 m0, s23, 0x2000
	s_add_u32 s70, s70, 0x40080
	s_addc_u32 s71, s71, 0
	s_add_i32 s23, s33, s74
	global_load_lds_dwordx4 v136, s[98:99]
	s_mov_b32 m0, s23
	s_nop 0
	global_load_lds_dwordx4 v132, s[70:71]
	s_add_i32 m0, s23, 0x2000
	s_nop 0
	global_load_lds_dwordx4 v136, s[70:71]
	s_mov_b32 m0, s82
	s_nop 0
	global_load_lds_dwordx4 v130, s[100:101]
	s_mov_b32 m0, s83
	s_nop 0
	global_load_lds_dwordx4 v134, s[100:101]
	s_waitcnt vmcnt(8)
	s_waitcnt lgkmcnt(0)
	s_barrier
	s_setprio 1
	v_mfma_f32_16x16x32_bf16 v[60:63], v[146:149], v[188:191], v[60:63]
	v_mfma_f32_16x16x32_bf16 v[56:59], v[164:167], v[188:191], v[56:59]
	v_mfma_f32_16x16x32_bf16 v[44:47], v[146:149], v[196:199], v[44:47]
	v_mfma_f32_16x16x32_bf16 v[40:43], v[164:167], v[196:199], v[40:43]
	v_mfma_f32_16x16x32_bf16 v[28:31], v[146:149], v[204:207], v[28:31]
	v_mfma_f32_16x16x32_bf16 v[24:27], v[164:167], v[204:207], v[24:27]
	v_mfma_f32_16x16x32_bf16 v[12:15], v[146:149], v[212:215], v[12:15]
	v_mfma_f32_16x16x32_bf16 v[8:11], v[164:167], v[212:215], v[8:11]
	v_mfma_f32_16x16x32_bf16 v[60:63], v[160:163], v[192:195], v[60:63]
	v_mfma_f32_16x16x32_bf16 v[56:59], v[168:171], v[192:195], v[56:59]
	v_mfma_f32_16x16x32_bf16 v[44:47], v[160:163], v[200:203], v[44:47]
	v_mfma_f32_16x16x32_bf16 v[40:43], v[168:171], v[200:203], v[40:43]
	v_mfma_f32_16x16x32_bf16 v[28:31], v[160:163], v[208:211], v[28:31]
	v_mfma_f32_16x16x32_bf16 v[24:27], v[168:171], v[208:211], v[24:27]
	v_mfma_f32_16x16x32_bf16 v[12:15], v[160:163], v[216:219], v[12:15]
	v_mfma_f32_16x16x32_bf16 v[8:11], v[168:171], v[216:219], v[8:11]
	v_mfma_f32_16x16x32_bf16 v[52:55], v[172:175], v[188:191], v[52:55]
	v_mfma_f32_16x16x32_bf16 v[48:51], v[180:183], v[188:191], v[48:51]
	v_mfma_f32_16x16x32_bf16 v[36:39], v[172:175], v[196:199], v[36:39]
	v_mfma_f32_16x16x32_bf16 v[32:35], v[180:183], v[196:199], v[32:35]
	v_mfma_f32_16x16x32_bf16 v[20:23], v[172:175], v[204:207], v[20:23]
	v_mfma_f32_16x16x32_bf16 v[16:19], v[180:183], v[204:207], v[16:19]
	v_mfma_f32_16x16x32_bf16 v[4:7], v[172:175], v[212:215], v[4:7]
	v_mfma_f32_16x16x32_bf16 v[0:3], v[180:183], v[212:215], v[0:3]
	v_mfma_f32_16x16x32_bf16 v[52:55], v[176:179], v[192:195], v[52:55]
	v_mfma_f32_16x16x32_bf16 v[48:51], v[184:187], v[192:195], v[48:51]
	v_mfma_f32_16x16x32_bf16 v[36:39], v[176:179], v[200:203], v[36:39]
	v_mfma_f32_16x16x32_bf16 v[32:35], v[184:187], v[200:203], v[32:35]
	v_mfma_f32_16x16x32_bf16 v[20:23], v[176:179], v[208:211], v[20:23]
	v_mfma_f32_16x16x32_bf16 v[16:19], v[184:187], v[208:211], v[16:19]
	v_mfma_f32_16x16x32_bf16 v[4:7], v[176:179], v[216:219], v[4:7]
	v_mfma_f32_16x16x32_bf16 v[0:3], v[184:187], v[216:219], v[0:3]
	s_setprio 0
	s_barrier
	s_add_i32 s92, s92, 2
	s_add_u32 s64, s64, 0x100
	s_addc_u32 s65, s65, 0
	s_add_u32 s90, s90, 0x100
	s_addc_u32 s91, s91, 0
	s_cmp_gt_u32 s92, 13
	s_cbranch_scc0 .LBB0_295
	s_and_b64 vcc, exec, s[14:15]
	s_cbranch_vccz .LBB0_298
	s_barrier

.LBB0_437:
	ds_read_b128 v[146:149], v139
	ds_read_b128 v[150:153], v139 offset:1024
	ds_read_b128 v[154:157], v139 offset:2048
	ds_read_b128 v[158:161], v139 offset:3072
	ds_read_b128 v[162:165], v141
	ds_read_b128 v[166:169], v141 offset:1024
	ds_read_b128 v[170:173], v141 offset:2048
	ds_read_b128 v[174:177], v141 offset:3072
	s_add_u32 s10, s6, s8
	s_addc_u32 s11, s7, s9
	s_add_u32 s10, s10, 0x2300100
	s_addc_u32 s11, s11, 0
	s_add_u32 s23, s69, s8
	s_addc_u32 s33, s70, s9
	s_cmpk_eq_i32 s8, 0x700
	s_cselect_b32 s13, s3, s11
	s_cselect_b32 s12, s2, s10
	s_cselect_b32 s11, s1, s33
	s_cselect_b32 s10, s0, s23
	s_mov_b32 m0, s72
	v_lshl_add_u64 v[210:211], v[134:135], 0, s[8:9]
	ds_read_b128 v[178:181], v142
	ds_read_b128 v[182:185], v142 offset:1024
	ds_read_b128 v[186:189], v142 offset:2048
	ds_read_b128 v[190:193], v142 offset:3072
	ds_read_b128 v[194:197], v142 offset:4096
	ds_read_b128 v[198:201], v142 offset:5120
	ds_read_b128 v[202:205], v142 offset:6144
	ds_read_b128 v[206:209], v142 offset:7168
	global_load_lds_dwordx4 v[210:211], off
	v_lshl_add_u64 v[210:211], v[136:137], 0, s[8:9]
	s_mov_b32 m0, s73
	s_nop 0
	global_load_lds_dwordx4 v[210:211], off
	s_waitcnt vmcnt(8)
	s_waitcnt lgkmcnt(0)
	s_barrier
	s_setprio 1
	v_mfma_f32_16x16x32_bf16 v[124:127], v[146:149], v[178:181], v[124:127]
	v_mfma_f32_16x16x32_bf16 v[120:123], v[154:157], v[178:181], v[120:123]
	v_mfma_f32_16x16x32_bf16 v[108:111], v[146:149], v[186:189], v[108:111]
	v_mfma_f32_16x16x32_bf16 v[104:107], v[154:157], v[186:189], v[104:107]
	v_mfma_f32_16x16x32_bf16 v[92:95], v[146:149], v[194:197], v[92:95]
	v_mfma_f32_16x16x32_bf16 v[88:91], v[154:157], v[194:197], v[88:91]
	v_mfma_f32_16x16x32_bf16 v[76:79], v[146:149], v[202:205], v[76:79]
	v_mfma_f32_16x16x32_bf16 v[72:75], v[154:157], v[202:205], v[72:75]
	v_mfma_f32_16x16x32_bf16 v[124:127], v[150:153], v[182:185], v[124:127]
	v_mfma_f32_16x16x32_bf16 v[120:123], v[158:161], v[182:185], v[120:123]
	v_mfma_f32_16x16x32_bf16 v[108:111], v[150:153], v[190:193], v[108:111]
	v_mfma_f32_16x16x32_bf16 v[104:107], v[158:161], v[190:193], v[104:107]
	v_mfma_f32_16x16x32_bf16 v[92:95], v[150:153], v[198:201], v[92:95]
	v_mfma_f32_16x16x32_bf16 v[88:91], v[158:161], v[198:201], v[88:91]
	v_mfma_f32_16x16x32_bf16 v[76:79], v[150:153], v[206:209], v[76:79]
	v_mfma_f32_16x16x32_bf16 v[72:75], v[158:161], v[206:209], v[72:75]
	v_mfma_f32_16x16x32_bf16 v[116:119], v[162:165], v[178:181], v[116:119]
	v_mfma_f32_16x16x32_bf16 v[112:115], v[170:173], v[178:181], v[112:115]
	v_mfma_f32_16x16x32_bf16 v[100:103], v[162:165], v[186:189], v[100:103]
	v_mfma_f32_16x16x32_bf16 v[96:99], v[170:173], v[186:189], v[96:99]
	v_mfma_f32_16x16x32_bf16 v[84:87], v[162:165], v[194:197], v[84:87]
	v_mfma_f32_16x16x32_bf16 v[80:83], v[170:173], v[194:197], v[80:83]
	v_mfma_f32_16x16x32_bf16 v[68:71], v[162:165], v[202:205], v[68:71]
	v_mfma_f32_16x16x32_bf16 v[64:67], v[170:173], v[202:205], v[64:67]
	v_mfma_f32_16x16x32_bf16 v[116:119], v[166:169], v[182:185], v[116:119]
	v_mfma_f32_16x16x32_bf16 v[112:115], v[174:177], v[182:185], v[112:115]
	v_mfma_f32_16x16x32_bf16 v[100:103], v[166:169], v[190:193], v[100:103]
	v_mfma_f32_16x16x32_bf16 v[96:99], v[174:177], v[190:193], v[96:99]
	v_mfma_f32_16x16x32_bf16 v[84:87], v[166:169], v[198:201], v[84:87]
	v_mfma_f32_16x16x32_bf16 v[80:83], v[174:177], v[198:201], v[80:83]
	v_mfma_f32_16x16x32_bf16 v[68:71], v[166:169], v[206:209], v[68:71]
	v_mfma_f32_16x16x32_bf16 v[64:67], v[174:177], v[206:209], v[64:67]
	s_setprio 0
	s_barrier
	s_add_u32 s98, s10, s4
	s_addc_u32 s99, s11, s5
	s_add_u32 s100, s12, s4
	s_addc_u32 s101, s13, s5
	s_mov_b32 m0, s74
	s_add_u32 s82, s10, 0x40000
	ds_read_b128 v[178:181], v142 offset:16384
	ds_read_b128 v[182:185], v142 offset:17408
	ds_read_b128 v[186:189], v142 offset:18432
	ds_read_b128 v[190:193], v142 offset:19456
	ds_read_b128 v[194:197], v142 offset:20480
	ds_read_b128 v[198:201], v142 offset:21504
	ds_read_b128 v[202:205], v142 offset:22528
	ds_read_b128 v[206:209], v142 offset:23552
	global_load_lds_dwordx4 v132, s[10:11]
	s_mov_b32 m0, s75
	s_addc_u32 s83, s11, 0
	global_load_lds_dwordx4 v130, s[10:11]
	s_mov_b32 m0, s76
	s_nop 0
	global_load_lds_dwordx4 v132, s[82:83]
	s_mov_b32 m0, s77
	s_nop 0
	global_load_lds_dwordx4 v130, s[82:83]
	s_mov_b32 m0, s17
	s_nop 0
	global_load_lds_dwordx4 v132, s[12:13]
	s_mov_b32 m0, s20
	s_nop 0
	global_load_lds_dwordx4 v130, s[12:13]
	s_waitcnt vmcnt(8)
	s_waitcnt lgkmcnt(0)
	s_barrier
	s_setprio 1
	v_mfma_f32_16x16x32_bf16 v[60:63], v[146:149], v[178:181], v[60:63]
	v_mfma_f32_16x16x32_bf16 v[56:59], v[154:157], v[178:181], v[56:59]
	v_mfma_f32_16x16x32_bf16 v[44:47], v[146:149], v[186:189], v[44:47]
	v_mfma_f32_16x16x32_bf16 v[40:43], v[154:157], v[186:189], v[40:43]
	v_mfma_f32_16x16x32_bf16 v[28:31], v[146:149], v[194:197], v[28:31]
	v_mfma_f32_16x16x32_bf16 v[24:27], v[154:157], v[194:197], v[24:27]
	v_mfma_f32_16x16x32_bf16 v[12:15], v[146:149], v[202:205], v[12:15]
	v_mfma_f32_16x16x32_bf16 v[8:11], v[154:157], v[202:205], v[8:11]
	v_mfma_f32_16x16x32_bf16 v[60:63], v[150:153], v[182:185], v[60:63]
	v_mfma_f32_16x16x32_bf16 v[56:59], v[158:161], v[182:185], v[56:59]
	v_mfma_f32_16x16x32_bf16 v[44:47], v[150:153], v[190:193], v[44:47]
	v_mfma_f32_16x16x32_bf16 v[40:43], v[158:161], v[190:193], v[40:43]
	v_mfma_f32_16x16x32_bf16 v[28:31], v[150:153], v[198:201], v[28:31]
	v_mfma_f32_16x16x32_bf16 v[24:27], v[158:161], v[198:201], v[24:27]
	v_mfma_f32_16x16x32_bf16 v[12:15], v[150:153], v[206:209], v[12:15]
	v_mfma_f32_16x16x32_bf16 v[8:11], v[158:161], v[206:209], v[8:11]
	v_mfma_f32_16x16x32_bf16 v[52:55], v[162:165], v[178:181], v[52:55]
	v_mfma_f32_16x16x32_bf16 v[48:51], v[170:173], v[178:181], v[48:51]
	v_mfma_f32_16x16x32_bf16 v[36:39], v[162:165], v[186:189], v[36:39]
	v_mfma_f32_16x16x32_bf16 v[32:35], v[170:173], v[186:189], v[32:35]
	v_mfma_f32_16x16x32_bf16 v[20:23], v[162:165], v[194:197], v[20:23]
	v_mfma_f32_16x16x32_bf16 v[16:19], v[170:173], v[194:197], v[16:19]
	v_mfma_f32_16x16x32_bf16 v[4:7], v[162:165], v[202:205], v[4:7]
	v_mfma_f32_16x16x32_bf16 v[0:3], v[170:173], v[202:205], v[0:3]
	v_mfma_f32_16x16x32_bf16 v[52:55], v[166:169], v[182:185], v[52:55]
	v_mfma_f32_16x16x32_bf16 v[48:51], v[174:177], v[182:185], v[48:51]
	v_mfma_f32_16x16x32_bf16 v[36:39], v[166:169], v[190:193], v[36:39]
	v_mfma_f32_16x16x32_bf16 v[32:35], v[174:177], v[190:193], v[32:35]
	v_mfma_f32_16x16x32_bf16 v[20:23], v[166:169], v[198:201], v[20:23]
	v_mfma_f32_16x16x32_bf16 v[16:19], v[174:177], v[198:201], v[16:19]
	v_mfma_f32_16x16x32_bf16 v[4:7], v[166:169], v[206:209], v[4:7]
	v_mfma_f32_16x16x32_bf16 v[0:3], v[174:177], v[206:209], v[0:3]
	s_setprio 0
	s_barrier
	ds_read_b128 v[146:149], v143
	ds_read_b128 v[150:153], v143 offset:1024
	ds_read_b128 v[154:157], v143 offset:2048
	ds_read_b128 v[158:161], v143 offset:3072
	ds_read_b128 v[162:165], v144
	ds_read_b128 v[166:169], v144 offset:1024
	ds_read_b128 v[170:173], v144 offset:2048
	ds_read_b128 v[174:177], v144 offset:3072
	s_add_u32 s12, s12, 0x40000
	s_addc_u32 s13, s13, 0
	s_mov_b32 m0, s21
	ds_read_b128 v[178:181], v142 offset:32768
	ds_read_b128 v[182:185], v142 offset:33792
	ds_read_b128 v[186:189], v142 offset:34816
	ds_read_b128 v[190:193], v142 offset:35840
	ds_read_b128 v[194:197], v142 offset:36864
	ds_read_b128 v[198:201], v142 offset:37888
	ds_read_b128 v[202:205], v142 offset:38912
	ds_read_b128 v[206:209], v142 offset:39936
	global_load_lds_dwordx4 v132, s[12:13]
	s_mov_b32 m0, s58
	s_nop 0
	global_load_lds_dwordx4 v130, s[12:13]
	s_waitcnt vmcnt(8)
	s_waitcnt lgkmcnt(0)
	s_barrier
	s_setprio 1
	v_mfma_f32_16x16x32_bf16 v[124:127], v[146:149], v[178:181], v[124:127]
	v_mfma_f32_16x16x32_bf16 v[120:123], v[154:157], v[178:181], v[120:123]
	v_mfma_f32_16x16x32_bf16 v[108:111], v[146:149], v[186:189], v[108:111]
	v_mfma_f32_16x16x32_bf16 v[104:107], v[154:157], v[186:189], v[104:107]
	v_mfma_f32_16x16x32_bf16 v[92:95], v[146:149], v[194:197], v[92:95]
	v_mfma_f32_16x16x32_bf16 v[88:91], v[154:157], v[194:197], v[88:91]
	v_mfma_f32_16x16x32_bf16 v[76:79], v[146:149], v[202:205], v[76:79]
	v_mfma_f32_16x16x32_bf16 v[72:75], v[154:157], v[202:205], v[72:75]
	v_mfma_f32_16x16x32_bf16 v[124:127], v[150:153], v[182:185], v[124:127]
	v_mfma_f32_16x16x32_bf16 v[120:123], v[158:161], v[182:185], v[120:123]
	v_mfma_f32_16x16x32_bf16 v[108:111], v[150:153], v[190:193], v[108:111]
	v_mfma_f32_16x16x32_bf16 v[104:107], v[158:161], v[190:193], v[104:107]
	v_mfma_f32_16x16x32_bf16 v[92:95], v[150:153], v[198:201], v[92:95]
	v_mfma_f32_16x16x32_bf16 v[88:91], v[158:161], v[198:201], v[88:91]
	v_mfma_f32_16x16x32_bf16 v[76:79], v[150:153], v[206:209], v[76:79]
	v_mfma_f32_16x16x32_bf16 v[72:75], v[158:161], v[206:209], v[72:75]
	v_mfma_f32_16x16x32_bf16 v[116:119], v[162:165], v[178:181], v[116:119]
	v_mfma_f32_16x16x32_bf16 v[112:115], v[170:173], v[178:181], v[112:115]
	v_mfma_f32_16x16x32_bf16 v[100:103], v[162:165], v[186:189], v[100:103]
	v_mfma_f32_16x16x32_bf16 v[96:99], v[170:173], v[186:189], v[96:99]
	v_mfma_f32_16x16x32_bf16 v[84:87], v[162:165], v[194:197], v[84:87]
	v_mfma_f32_16x16x32_bf16 v[80:83], v[170:173], v[194:197], v[80:83]
	v_mfma_f32_16x16x32_bf16 v[68:71], v[162:165], v[202:205], v[68:71]
	v_mfma_f32_16x16x32_bf16 v[64:67], v[170:173], v[202:205], v[64:67]
	v_mfma_f32_16x16x32_bf16 v[116:119], v[166:169], v[182:185], v[116:119]
	v_mfma_f32_16x16x32_bf16 v[112:115], v[174:177], v[182:185], v[112:115]
	v_mfma_f32_16x16x32_bf16 v[100:103], v[166:169], v[190:193], v[100:103]
	v_mfma_f32_16x16x32_bf16 v[96:99], v[174:177], v[190:193], v[96:99]
	v_mfma_f32_16x16x32_bf16 v[84:87], v[166:169], v[198:201], v[84:87]
	v_mfma_f32_16x16x32_bf16 v[80:83], v[174:177], v[198:201], v[80:83]
	v_mfma_f32_16x16x32_bf16 v[68:71], v[166:169], v[206:209], v[68:71]
	v_mfma_f32_16x16x32_bf16 v[64:67], v[174:177], v[206:209], v[64:67]
	s_setprio 0
	s_barrier
	s_mov_b32 m0, s78
	s_add_u32 s10, s10, 0x40080
	ds_read_b128 v[178:181], v142 offset:49152
	ds_read_b128 v[182:185], v142 offset:50176
	ds_read_b128 v[186:189], v142 offset:51200
	ds_read_b128 v[190:193], v142 offset:52224
	ds_read_b128 v[194:197], v142 offset:53248
	ds_read_b128 v[198:201], v142 offset:54272
	ds_read_b128 v[202:205], v142 offset:55296
	ds_read_b128 v[206:209], v142 offset:56320
	global_load_lds_dwordx4 v132, s[98:99]
	s_mov_b32 m0, s79
	s_addc_u32 s11, s11, 0
	global_load_lds_dwordx4 v130, s[98:99]
	s_mov_b32 m0, s80
	s_nop 0
	global_load_lds_dwordx4 v132, s[10:11]
	s_mov_b32 m0, s81
	s_nop 0
	global_load_lds_dwordx4 v130, s[10:11]
	s_mov_b32 m0, s65
	s_nop 0
	global_load_lds_dwordx4 v132, s[100:101]
	s_mov_b32 m0, s68
	s_nop 0
	global_load_lds_dwordx4 v130, s[100:101]
	s_waitcnt vmcnt(8)
	s_waitcnt lgkmcnt(0)
	s_barrier
	s_setprio 1
	v_mfma_f32_16x16x32_bf16 v[60:63], v[146:149], v[178:181], v[60:63]
	v_mfma_f32_16x16x32_bf16 v[56:59], v[154:157], v[178:181], v[56:59]
	v_mfma_f32_16x16x32_bf16 v[44:47], v[146:149], v[186:189], v[44:47]
	v_mfma_f32_16x16x32_bf16 v[40:43], v[154:157], v[186:189], v[40:43]
	v_mfma_f32_16x16x32_bf16 v[28:31], v[146:149], v[194:197], v[28:31]
	v_mfma_f32_16x16x32_bf16 v[24:27], v[154:157], v[194:197], v[24:27]
	v_mfma_f32_16x16x32_bf16 v[12:15], v[146:149], v[202:205], v[12:15]
	v_mfma_f32_16x16x32_bf16 v[8:11], v[154:157], v[202:205], v[8:11]
	v_mfma_f32_16x16x32_bf16 v[60:63], v[150:153], v[182:185], v[60:63]
	v_mfma_f32_16x16x32_bf16 v[56:59], v[158:161], v[182:185], v[56:59]
	v_mfma_f32_16x16x32_bf16 v[44:47], v[150:153], v[190:193], v[44:47]
	v_mfma_f32_16x16x32_bf16 v[40:43], v[158:161], v[190:193], v[40:43]
	v_mfma_f32_16x16x32_bf16 v[28:31], v[150:153], v[198:201], v[28:31]
	v_mfma_f32_16x16x32_bf16 v[24:27], v[158:161], v[198:201], v[24:27]
	v_mfma_f32_16x16x32_bf16 v[12:15], v[150:153], v[206:209], v[12:15]
	v_mfma_f32_16x16x32_bf16 v[8:11], v[158:161], v[206:209], v[8:11]
	v_mfma_f32_16x16x32_bf16 v[52:55], v[162:165], v[178:181], v[52:55]
	v_mfma_f32_16x16x32_bf16 v[48:51], v[170:173], v[178:181], v[48:51]
	v_mfma_f32_16x16x32_bf16 v[36:39], v[162:165], v[186:189], v[36:39]
	v_mfma_f32_16x16x32_bf16 v[32:35], v[170:173], v[186:189], v[32:35]
	v_mfma_f32_16x16x32_bf16 v[20:23], v[162:165], v[194:197], v[20:23]
	v_mfma_f32_16x16x32_bf16 v[16:19], v[170:173], v[194:197], v[16:19]
	v_mfma_f32_16x16x32_bf16 v[4:7], v[162:165], v[202:205], v[4:7]
	v_mfma_f32_16x16x32_bf16 v[0:3], v[170:173], v[202:205], v[0:3]
	v_mfma_f32_16x16x32_bf16 v[52:55], v[166:169], v[182:185], v[52:55]
	v_mfma_f32_16x16x32_bf16 v[48:51], v[174:177], v[182:185], v[48:51]
	v_mfma_f32_16x16x32_bf16 v[36:39], v[166:169], v[190:193], v[36:39]
	v_mfma_f32_16x16x32_bf16 v[32:35], v[174:177], v[190:193], v[32:35]
	v_mfma_f32_16x16x32_bf16 v[20:23], v[166:169], v[198:201], v[20:23]
	v_mfma_f32_16x16x32_bf16 v[16:19], v[174:177], v[198:201], v[16:19]
	v_mfma_f32_16x16x32_bf16 v[4:7], v[166:169], v[206:209], v[4:7]
	v_mfma_f32_16x16x32_bf16 v[0:3], v[174:177], v[206:209], v[0:3]
	s_setprio 0
	s_barrier
	s_add_i32 s71, s71, 2
	s_add_u32 s8, s8, 0x100
	s_addc_u32 s9, s9, 0
	s_cmp_gt_u32 s71, 13
	s_cbranch_scc0 .LBB0_437
	s_add_u32 s4, s28, 0x2f41000
	s_addc_u32 s5, s29, 0
	s_lshl_b32 s0, s16, 8
	s_add_i32 s64, s64, s0
	v_or_b32_e32 v130, s64, v140
	v_mov_b32_e32 v131, 0
	v_lshl_add_u64 v[132:133], v[130:131], 2, s[4:5]
	global_load_dword v149, v[132:133], off
	v_lshl_or_b32 v134, v138, 2, s59
	v_mov_b32_e32 v148, 0x358637bd
	s_lshl_b32 s13, s15, 8
	s_mov_b32 s6, 0x800000
	s_movk_i32 s0, 0x36c
	v_or_b32_e32 v146, s13, v134
	s_and_b32 s9, s13, 0x300
	v_mov_b32_e32 v150, s13
	s_lshl_b32 s13, s64, 2
	v_mov_b32_e32 v142, 0x80
	s_movk_i32 s10, 0xec
	v_lshlrev_b32_e32 v138, 1, v134
	v_bitop3_b32 v134, v134, s0, v150 bitop3:0xc8
	s_and_b32 s0, s13, 0xfffffc00
	v_bitop3_b32 v154, v146, s10, v142 bitop3:0xc8
	s_or_b32 s10, s0, s9
	s_mov_b32 s1, 0x4880000
	s_cmp_gt_u32 s15, 3
	v_mov_b32_e32 v136, 0xcf
	s_mov_b32 s2, 0x2b00000
	s_cselect_b32 s0, s1, 0x4080000
	s_movk_i32 s3, 0x37c
	s_movk_i32 s8, 0x3ec
	v_bitop3_b32 v152, s64, v136, v140 bitop3:0xc8
	s_cselect_b32 s1, s2, 0x2700000
	s_add_u32 s2, s26, s0
	v_bitop3_b32 v136, v146, s3, 16 bitop3:0xc8
	v_bitop3_b32 v153, v146, s8, v142 bitop3:0xc8
	v_or_b32_e32 v152, s10, v152
	s_addc_u32 s3, s27, 0
	s_movk_i32 s7, 0x7c
	s_movk_i32 s11, 0x3fc
	v_mov_b32_e32 v144, 0x90
	s_movk_i32 s12, 0xfc
	v_lshlrev_b64 v[150:151], 12, v[130:131]
	v_lshlrev_b32_e32 v142, 2, v153
	v_ashrrev_i32_e32 v153, 31, v152
	s_add_u32 s0, s28, s1
	v_mov_b32_e32 v147, v131
	v_bitop3_b32 v140, v146, s7, 16 bitop3:0xc8
	v_bitop3_b32 v155, v146, s11, v144 bitop3:0xc8
	v_bitop3_b32 v167, v146, s12, v144 bitop3:0xc8
	v_lshlrev_b32_e32 v146, 2, v134
	v_lshlrev_b64 v[152:153], 9, v[152:153]
	v_lshl_add_u64 v[150:151], s[2:3], 0, v[150:151]
	s_addc_u32 s1, s29, 0
	v_mov_b32_e32 v139, v131
	v_lshlrev_b32_e32 v144, 2, v136
	v_lshlrev_b32_e32 v134, 1, v140
	v_lshlrev_b32_e32 v136, 1, v154
	v_lshlrev_b32_e32 v140, 2, v155
	v_lshl_add_u64 v[154:155], v[150:151], 0, v[146:147]
	v_lshl_add_u64 v[152:153], s[0:1], 0, v[152:153]
	v_mov_b32_e32 v145, v131
	v_mov_b32_e32 v135, v131
	v_mov_b32_e32 v143, v131
	v_mov_b32_e32 v137, v131
	v_lshl_add_u64 v[156:157], v[150:151], 0, v[144:145]
	v_lshl_add_u64 v[162:163], v[152:153], 0, v[134:135]
	v_mov_b32_e32 v141, v131
	v_lshl_add_u64 v[158:159], v[150:151], 0, v[142:143]
	v_lshl_add_u64 v[164:165], v[152:153], 0, v[136:137]
	v_lshl_add_u64 v[150:151], v[150:151], 0, v[140:141]
	s_movk_i32 s7, 0xdf
	s_movk_i32 s8, 0xef
	s_cmpk_lt_u32 s14, 0x100
	s_waitcnt vmcnt(0)
	v_fmamk_f32 v149, v149, 0x3a800000, v148
	v_mul_f32_e32 v160, 0x4b800000, v149
	v_cmp_gt_f32_e32 vcc, s6, v149
	s_nop 1
	v_cndmask_b32_e32 v149, v149, v160, vcc
	v_rsq_f32_e32 v149, v149
	v_lshl_add_u64 v[160:161], v[152:153], 0, v[138:139]
	v_mul_f32_e32 v166, 0x45800000, v149
	v_cndmask_b32_e32 v166, v149, v166, vcc
	v_pk_mul_f32 v[126:127], v[126:127], v[166:167] op_sel_hi:[1,0]
	v_pk_mul_f32 v[124:125], v[124:125], v[166:167] op_sel_hi:[1,0]
	v_pk_mul_f32 v[120:121], v[120:121], v[166:167] op_sel_hi:[1,0]
	global_store_dwordx4 v[154:155], v[124:127], off
	v_pk_mul_f32 v[122:123], v[122:123], v[166:167] op_sel_hi:[1,0]
	v_pk_mul_f32 v[116:117], v[116:117], v[166:167] op_sel_hi:[1,0]
	v_cvt_pk_bf16_f32 v124, v124, v125
	v_cvt_pk_bf16_f32 v125, v126, v127
	global_store_dwordx2 v[160:161], v[124:125], off
	global_store_dwordx4 v[156:157], v[120:123], off
	v_pk_mul_f32 v[118:119], v[118:119], v[166:167] op_sel_hi:[1,0]
	v_pk_mul_f32 v[112:113], v[112:113], v[166:167] op_sel_hi:[1,0]
	v_cvt_pk_bf16_f32 v120, v120, v121
	v_cvt_pk_bf16_f32 v121, v122, v123
	global_store_dwordx2 v[162:163], v[120:121], off
	global_store_dwordx4 v[158:159], v[116:119], off
	v_pk_mul_f32 v[114:115], v[114:115], v[166:167] op_sel_hi:[1,0]
	v_bitop3_b32 v120, v130, s7, 16 bitop3:0xc8
	v_cvt_pk_bf16_f32 v116, v116, v117
	v_cvt_pk_bf16_f32 v117, v118, v119
	global_store_dwordx2 v[164:165], v[116:117], off
	global_store_dwordx4 v[150:151], v[112:115], off
	v_cvt_pk_bf16_f32 v116, v112, v113
	v_cvt_pk_bf16_f32 v117, v114, v115
	v_or_b32_e32 v120, s10, v120
	v_ashrrev_i32_e32 v121, 31, v120
	v_lshlrev_b32_e32 v112, 1, v167
	v_mov_b32_e32 v113, v131
	v_lshl_add_u64 v[114:115], v[152:153], 0, v[112:113]
	global_store_dwordx2 v[114:115], v[116:117], off
	v_or_b32_e32 v114, 16, v130
	v_mov_b32_e32 v115, v131
	v_lshl_add_u64 v[116:117], v[114:115], 2, s[4:5]
	global_load_dword v149, v[116:117], off
	v_lshlrev_b64 v[114:115], 12, v[114:115]
	v_lshlrev_b64 v[120:121], 9, v[120:121]
	v_lshl_add_u64 v[114:115], s[2:3], 0, v[114:115]
	v_lshl_add_u64 v[122:123], v[114:115], 0, v[146:147]
	v_lshl_add_u64 v[120:121], s[0:1], 0, v[120:121]
	v_lshl_add_u64 v[150:151], v[120:121], 0, v[138:139]
	v_lshl_add_u64 v[124:125], v[114:115], 0, v[144:145]
	v_mov_b32_e32 v117, v131
	v_or_b32_e32 v116, 32, v130
	v_lshl_add_u64 v[126:127], v[114:115], 0, v[142:143]
	v_lshl_add_u64 v[154:155], v[120:121], 0, v[136:137]
	v_lshl_add_u64 v[118:119], v[116:117], 2, s[4:5]
	v_lshl_add_u64 v[114:115], v[114:115], 0, v[140:141]
	s_waitcnt vmcnt(0)
	v_fmamk_f32 v149, v149, 0x3a800000, v148
	v_mul_f32_e32 v152, 0x4b800000, v149
	v_cmp_gt_f32_e32 vcc, s6, v149
	s_nop 1
	v_cndmask_b32_e32 v149, v149, v152, vcc
	v_rsq_f32_e32 v149, v149
	v_lshl_add_u64 v[152:153], v[120:121], 0, v[134:135]
	v_lshl_add_u64 v[120:121], v[120:121], 0, v[112:113]
	v_mul_f32_e32 v156, 0x45800000, v149
	v_cndmask_b32_e32 v156, v149, v156, vcc
	v_pk_mul_f32 v[110:111], v[110:111], v[156:157] op_sel_hi:[1,0]
	v_pk_mul_f32 v[108:109], v[108:109], v[156:157] op_sel_hi:[1,0]
	v_pk_mul_f32 v[104:105], v[104:105], v[156:157] op_sel_hi:[1,0]
	global_store_dwordx4 v[122:123], v[108:111], off
	v_pk_mul_f32 v[106:107], v[106:107], v[156:157] op_sel_hi:[1,0]
	v_pk_mul_f32 v[100:101], v[100:101], v[156:157] op_sel_hi:[1,0]
	v_cvt_pk_bf16_f32 v108, v108, v109
	v_cvt_pk_bf16_f32 v109, v110, v111
	global_store_dwordx2 v[150:151], v[108:109], off
	global_store_dwordx4 v[124:125], v[104:107], off
	v_pk_mul_f32 v[102:103], v[102:103], v[156:157] op_sel_hi:[1,0]
	v_pk_mul_f32 v[96:97], v[96:97], v[156:157] op_sel_hi:[1,0]
	v_cvt_pk_bf16_f32 v104, v104, v105
	v_cvt_pk_bf16_f32 v105, v106, v107
	global_store_dwordx2 v[152:153], v[104:105], off
	global_store_dwordx4 v[126:127], v[100:103], off
	v_pk_mul_f32 v[98:99], v[98:99], v[156:157] op_sel_hi:[1,0]
	s_nop 0
	v_cvt_pk_bf16_f32 v100, v100, v101
	v_cvt_pk_bf16_f32 v101, v102, v103
	global_store_dwordx2 v[154:155], v[100:101], off
	global_store_dwordx4 v[114:115], v[96:99], off
	v_bitop3_b32 v102, v130, s8, 32 bitop3:0xc8
	v_or_b32_e32 v102, s10, v102
	v_cvt_pk_bf16_f32 v96, v96, v97
	v_cvt_pk_bf16_f32 v97, v98, v99
	global_store_dwordx2 v[120:121], v[96:97], off
	global_load_dword v114, v[118:119], off
	v_lshlrev_b64 v[98:99], 12, v[116:117]
	v_ashrrev_i32_e32 v103, 31, v102
	v_lshlrev_b64 v[102:103], 9, v[102:103]
	v_lshl_add_u64 v[98:99], s[2:3], 0, v[98:99]
	v_lshl_add_u64 v[104:105], v[98:99], 0, v[146:147]
	v_lshl_add_u64 v[102:103], s[0:1], 0, v[102:103]
	v_lshl_add_u64 v[110:111], v[102:103], 0, v[138:139]
	v_lshl_add_u64 v[106:107], v[98:99], 0, v[144:145]
	v_mov_b32_e32 v97, v131
	v_or_b32_e32 v96, 48, v130
	v_lshl_add_u64 v[108:109], v[98:99], 0, v[142:143]
	v_lshl_add_u64 v[116:117], v[102:103], 0, v[136:137]
	v_lshl_add_u64 v[100:101], v[96:97], 2, s[4:5]
	v_lshl_add_u64 v[98:99], v[98:99], 0, v[140:141]
	s_movk_i32 s4, 0xff
	s_movk_i32 s5, 0xcf
	s_waitcnt vmcnt(0)
	v_fmamk_f32 v114, v114, 0x3a800000, v148
	v_mul_f32_e32 v115, 0x4b800000, v114
	v_cmp_gt_f32_e32 vcc, s6, v114
	s_nop 1
	v_cndmask_b32_e32 v114, v114, v115, vcc
	v_rsq_f32_e32 v118, v114
	v_lshl_add_u64 v[114:115], v[102:103], 0, v[134:135]
	v_lshl_add_u64 v[102:103], v[102:103], 0, v[112:113]
	v_mul_f32_e32 v119, 0x45800000, v118
	v_cndmask_b32_e32 v118, v118, v119, vcc
	v_pk_mul_f32 v[94:95], v[94:95], v[118:119] op_sel_hi:[1,0]
	v_pk_mul_f32 v[92:93], v[92:93], v[118:119] op_sel_hi:[1,0]
	v_pk_mul_f32 v[88:89], v[88:89], v[118:119] op_sel_hi:[1,0]
	global_store_dwordx4 v[104:105], v[92:95], off
	v_pk_mul_f32 v[90:91], v[90:91], v[118:119] op_sel_hi:[1,0]
	v_pk_mul_f32 v[84:85], v[84:85], v[118:119] op_sel_hi:[1,0]
	v_cvt_pk_bf16_f32 v92, v92, v93
	v_cvt_pk_bf16_f32 v93, v94, v95
	global_store_dwordx2 v[110:111], v[92:93], off
	global_store_dwordx4 v[106:107], v[88:91], off
	v_pk_mul_f32 v[86:87], v[86:87], v[118:119] op_sel_hi:[1,0]
	v_pk_mul_f32 v[80:81], v[80:81], v[118:119] op_sel_hi:[1,0]
	v_cvt_pk_bf16_f32 v88, v88, v89
	v_cvt_pk_bf16_f32 v89, v90, v91
	global_store_dwordx2 v[114:115], v[88:89], off
	global_store_dwordx4 v[108:109], v[84:87], off
	v_pk_mul_f32 v[82:83], v[82:83], v[118:119] op_sel_hi:[1,0]
	s_nop 0
	v_cvt_pk_bf16_f32 v84, v84, v85
	v_cvt_pk_bf16_f32 v85, v86, v87
	global_store_dwordx2 v[116:117], v[84:85], off
	global_store_dwordx4 v[98:99], v[80:83], off
	s_nop 1
	v_cvt_pk_bf16_f32 v80, v80, v81
	v_cvt_pk_bf16_f32 v81, v82, v83
	global_store_dwordx2 v[102:103], v[80:81], off
	global_load_dword v92, v[100:101], off
	v_lshlrev_b64 v[80:81], 12, v[96:97]
	v_bitop3_b32 v82, v130, s4, 48 bitop3:0xc8
	v_or_b32_e32 v82, s10, v82
	v_ashrrev_i32_e32 v83, 31, v82
	v_lshlrev_b64 v[82:83], 9, v[82:83]
	v_lshl_add_u64 v[80:81], s[2:3], 0, v[80:81]
	v_lshl_add_u64 v[84:85], v[80:81], 0, v[146:147]
	v_lshl_add_u64 v[82:83], s[0:1], 0, v[82:83]
	v_lshl_add_u64 v[90:91], v[82:83], 0, v[138:139]
	v_lshl_add_u64 v[86:87], v[80:81], 0, v[144:145]
	v_lshl_add_u64 v[88:89], v[80:81], 0, v[142:143]
	v_lshl_add_u64 v[94:95], v[82:83], 0, v[136:137]
	v_lshl_add_u64 v[80:81], v[80:81], 0, v[140:141]
	s_waitcnt vmcnt(0)
	v_fmamk_f32 v92, v92, 0x3a800000, v148
	v_mul_f32_e32 v93, 0x4b800000, v92
	v_cmp_gt_f32_e32 vcc, s6, v92
	s_nop 1
	v_cndmask_b32_e32 v92, v92, v93, vcc
	v_rsq_f32_e32 v96, v92
	v_lshl_add_u64 v[92:93], v[82:83], 0, v[134:135]
	v_lshl_add_u64 v[82:83], v[82:83], 0, v[112:113]
	v_mul_f32_e32 v97, 0x45800000, v96
	v_cndmask_b32_e32 v96, v96, v97, vcc
	v_pk_mul_f32 v[78:79], v[78:79], v[96:97] op_sel_hi:[1,0]
	v_pk_mul_f32 v[76:77], v[76:77], v[96:97] op_sel_hi:[1,0]
	v_pk_mul_f32 v[72:73], v[72:73], v[96:97] op_sel_hi:[1,0]
	global_store_dwordx4 v[84:85], v[76:79], off
	v_pk_mul_f32 v[74:75], v[74:75], v[96:97] op_sel_hi:[1,0]
	v_pk_mul_f32 v[68:69], v[68:69], v[96:97] op_sel_hi:[1,0]
	v_cvt_pk_bf16_f32 v76, v76, v77
	v_cvt_pk_bf16_f32 v77, v78, v79
	global_store_dwordx2 v[90:91], v[76:77], off
	global_store_dwordx4 v[86:87], v[72:75], off
	v_pk_mul_f32 v[70:71], v[70:71], v[96:97] op_sel_hi:[1,0]
	v_pk_mul_f32 v[64:65], v[64:65], v[96:97] op_sel_hi:[1,0]
	v_cvt_pk_bf16_f32 v72, v72, v73
	v_cvt_pk_bf16_f32 v73, v74, v75
	global_store_dwordx2 v[92:93], v[72:73], off
	global_store_dwordx4 v[88:89], v[68:71], off
	v_pk_mul_f32 v[66:67], v[66:67], v[96:97] op_sel_hi:[1,0]
	s_nop 0
	v_cvt_pk_bf16_f32 v68, v68, v69
	v_cvt_pk_bf16_f32 v69, v70, v71
	global_store_dwordx2 v[94:95], v[68:69], off
	global_store_dwordx4 v[80:81], v[64:67], off
	s_nop 1
	v_cvt_pk_bf16_f32 v64, v64, v65
	v_cvt_pk_bf16_f32 v65, v66, v67
	global_store_dwordx2 v[82:83], v[64:65], off
	global_load_dword v76, v[132:133], off offset:512
	v_add_u32_e32 v64, 0x80, v130
	v_mov_b32_e32 v65, v131
	v_lshlrev_b32_e32 v68, 2, v64
	v_lshlrev_b64 v[66:67], 12, v[64:65]
	v_and_b32_e32 v65, 0xfffffc00, v68
	v_or_b32_e32 v81, s9, v65
	v_and_or_b32 v64, v64, s5, v81
	v_ashrrev_i32_e32 v65, 31, v64
	v_lshlrev_b64 v[64:65], 9, v[64:65]
	v_lshl_add_u64 v[66:67], s[2:3], 0, v[66:67]
	v_lshl_add_u64 v[68:69], v[66:67], 0, v[146:147]
	v_lshl_add_u64 v[64:65], s[0:1], 0, v[64:65]
	v_lshl_add_u64 v[74:75], v[64:65], 0, v[138:139]
	v_lshl_add_u64 v[70:71], v[66:67], 0, v[144:145]
	v_lshl_add_u64 v[72:73], v[66:67], 0, v[142:143]
	v_lshl_add_u64 v[78:79], v[64:65], 0, v[136:137]
	v_lshl_add_u64 v[66:67], v[66:67], 0, v[140:141]
	s_waitcnt vmcnt(0)
	v_fmamk_f32 v76, v76, 0x3a800000, v148
	v_mul_f32_e32 v77, 0x4b800000, v76
	v_cmp_gt_f32_e32 vcc, s6, v76
	s_nop 1
	v_cndmask_b32_e32 v76, v76, v77, vcc
	v_rsq_f32_e32 v80, v76
	v_lshl_add_u64 v[76:77], v[64:65], 0, v[134:135]
	v_lshl_add_u64 v[64:65], v[64:65], 0, v[112:113]
	v_mul_f32_e32 v82, 0x45800000, v80
	v_cndmask_b32_e32 v80, v80, v82, vcc
	v_pk_mul_f32 v[62:63], v[62:63], v[80:81] op_sel_hi:[1,0]
	v_pk_mul_f32 v[60:61], v[60:61], v[80:81] op_sel_hi:[1,0]
	v_pk_mul_f32 v[56:57], v[56:57], v[80:81] op_sel_hi:[1,0]
	global_store_dwordx4 v[68:69], v[60:63], off
	v_pk_mul_f32 v[58:59], v[58:59], v[80:81] op_sel_hi:[1,0]
	v_pk_mul_f32 v[52:53], v[52:53], v[80:81] op_sel_hi:[1,0]
	v_cvt_pk_bf16_f32 v60, v60, v61
	v_cvt_pk_bf16_f32 v61, v62, v63
	global_store_dwordx2 v[74:75], v[60:61], off
	global_store_dwordx4 v[70:71], v[56:59], off
	v_pk_mul_f32 v[54:55], v[54:55], v[80:81] op_sel_hi:[1,0]
	v_pk_mul_f32 v[48:49], v[48:49], v[80:81] op_sel_hi:[1,0]
	v_cvt_pk_bf16_f32 v56, v56, v57
	v_cvt_pk_bf16_f32 v57, v58, v59
	global_store_dwordx2 v[76:77], v[56:57], off
	global_store_dwordx4 v[72:73], v[52:55], off
	v_pk_mul_f32 v[50:51], v[50:51], v[80:81] op_sel_hi:[1,0]
	s_nop 0
	v_cvt_pk_bf16_f32 v52, v52, v53
	v_cvt_pk_bf16_f32 v53, v54, v55
	global_store_dwordx2 v[78:79], v[52:53], off
	global_store_dwordx4 v[66:67], v[48:51], off
	s_nop 1
	v_cvt_pk_bf16_f32 v48, v48, v49
	v_cvt_pk_bf16_f32 v49, v50, v51
	global_store_dwordx2 v[64:65], v[48:49], off
	global_load_dword v60, v[132:133], off offset:576
	v_mov_b32_e32 v49, v131
	v_add_u32_e32 v48, 0x90, v130
	v_lshlrev_b64 v[50:51], 12, v[48:49]
	v_and_or_b32 v48, v48, s7, v81
	v_ashrrev_i32_e32 v49, 31, v48
	v_lshlrev_b64 v[48:49], 9, v[48:49]
	v_lshl_add_u64 v[50:51], s[2:3], 0, v[50:51]
	v_lshl_add_u64 v[52:53], v[50:51], 0, v[146:147]
	v_lshl_add_u64 v[48:49], s[0:1], 0, v[48:49]
	v_lshl_add_u64 v[58:59], v[48:49], 0, v[138:139]
	v_lshl_add_u64 v[54:55], v[50:51], 0, v[144:145]
	v_lshl_add_u64 v[56:57], v[50:51], 0, v[142:143]
	v_lshl_add_u64 v[62:63], v[48:49], 0, v[136:137]
	v_lshl_add_u64 v[50:51], v[50:51], 0, v[140:141]
	s_waitcnt vmcnt(0)
	v_fmamk_f32 v60, v60, 0x3a800000, v148
	v_mul_f32_e32 v61, 0x4b800000, v60
	v_cmp_gt_f32_e32 vcc, s6, v60
	s_nop 1
	v_cndmask_b32_e32 v60, v60, v61, vcc
	v_rsq_f32_e32 v64, v60
	v_lshl_add_u64 v[60:61], v[48:49], 0, v[134:135]
	v_lshl_add_u64 v[48:49], v[48:49], 0, v[112:113]
	v_mul_f32_e32 v65, 0x45800000, v64
	v_cndmask_b32_e32 v64, v64, v65, vcc
	v_pk_mul_f32 v[46:47], v[46:47], v[64:65] op_sel_hi:[1,0]
	v_pk_mul_f32 v[44:45], v[44:45], v[64:65] op_sel_hi:[1,0]
	v_pk_mul_f32 v[40:41], v[40:41], v[64:65] op_sel_hi:[1,0]
	global_store_dwordx4 v[52:53], v[44:47], off
	v_pk_mul_f32 v[42:43], v[42:43], v[64:65] op_sel_hi:[1,0]
	v_pk_mul_f32 v[36:37], v[36:37], v[64:65] op_sel_hi:[1,0]
	v_cvt_pk_bf16_f32 v44, v44, v45
	v_cvt_pk_bf16_f32 v45, v46, v47
	global_store_dwordx2 v[58:59], v[44:45], off
	global_store_dwordx4 v[54:55], v[40:43], off
	v_pk_mul_f32 v[38:39], v[38:39], v[64:65] op_sel_hi:[1,0]
	v_pk_mul_f32 v[32:33], v[32:33], v[64:65] op_sel_hi:[1,0]
	v_cvt_pk_bf16_f32 v40, v40, v41
	v_cvt_pk_bf16_f32 v41, v42, v43
	global_store_dwordx2 v[60:61], v[40:41], off
	global_store_dwordx4 v[56:57], v[36:39], off
	v_pk_mul_f32 v[34:35], v[34:35], v[64:65] op_sel_hi:[1,0]
	s_nop 0
	v_cvt_pk_bf16_f32 v36, v36, v37
	v_cvt_pk_bf16_f32 v37, v38, v39
	global_store_dwordx2 v[62:63], v[36:37], off
	global_store_dwordx4 v[50:51], v[32:35], off
	s_nop 1
	v_cvt_pk_bf16_f32 v32, v32, v33
	v_cvt_pk_bf16_f32 v33, v34, v35
	global_store_dwordx2 v[48:49], v[32:33], off
	global_load_dword v44, v[132:133], off offset:640
	v_mov_b32_e32 v33, v131
	v_add_u32_e32 v32, 0xa0, v130
	v_lshlrev_b64 v[34:35], 12, v[32:33]
	v_and_or_b32 v32, v32, s8, v81
	v_ashrrev_i32_e32 v33, 31, v32
	v_lshlrev_b64 v[32:33], 9, v[32:33]
	v_lshl_add_u64 v[34:35], s[2:3], 0, v[34:35]
	v_lshl_add_u64 v[36:37], v[34:35], 0, v[146:147]
	v_lshl_add_u64 v[32:33], s[0:1], 0, v[32:33]
	v_lshl_add_u64 v[42:43], v[32:33], 0, v[138:139]
	v_lshl_add_u64 v[38:39], v[34:35], 0, v[144:145]
	v_lshl_add_u64 v[40:41], v[34:35], 0, v[142:143]
	v_lshl_add_u64 v[46:47], v[32:33], 0, v[136:137]
	v_lshl_add_u64 v[34:35], v[34:35], 0, v[140:141]
	v_add_u32_e32 v130, 0xb0, v130
	s_waitcnt vmcnt(0)
	v_fmamk_f32 v44, v44, 0x3a800000, v148
	v_mul_f32_e32 v45, 0x4b800000, v44
	v_cmp_gt_f32_e32 vcc, s6, v44
	s_nop 1
	v_cndmask_b32_e32 v44, v44, v45, vcc
	v_rsq_f32_e32 v48, v44
	v_lshl_add_u64 v[44:45], v[32:33], 0, v[134:135]
	v_lshl_add_u64 v[32:33], v[32:33], 0, v[112:113]
	v_mul_f32_e32 v49, 0x45800000, v48
	v_cndmask_b32_e32 v48, v48, v49, vcc
	v_pk_mul_f32 v[30:31], v[30:31], v[48:49] op_sel_hi:[1,0]
	v_pk_mul_f32 v[28:29], v[28:29], v[48:49] op_sel_hi:[1,0]
	v_pk_mul_f32 v[24:25], v[24:25], v[48:49] op_sel_hi:[1,0]
	global_store_dwordx4 v[36:37], v[28:31], off
	v_pk_mul_f32 v[26:27], v[26:27], v[48:49] op_sel_hi:[1,0]
	v_pk_mul_f32 v[20:21], v[20:21], v[48:49] op_sel_hi:[1,0]
	v_cvt_pk_bf16_f32 v28, v28, v29
	v_cvt_pk_bf16_f32 v29, v30, v31
	global_store_dwordx2 v[42:43], v[28:29], off
	global_store_dwordx4 v[38:39], v[24:27], off
	v_pk_mul_f32 v[22:23], v[22:23], v[48:49] op_sel_hi:[1,0]
	v_pk_mul_f32 v[16:17], v[16:17], v[48:49] op_sel_hi:[1,0]
	v_cvt_pk_bf16_f32 v24, v24, v25
	v_cvt_pk_bf16_f32 v25, v26, v27
	global_store_dwordx2 v[44:45], v[24:25], off
	global_store_dwordx4 v[40:41], v[20:23], off
	v_pk_mul_f32 v[18:19], v[18:19], v[48:49] op_sel_hi:[1,0]
	s_nop 0
	v_cvt_pk_bf16_f32 v20, v20, v21
	v_cvt_pk_bf16_f32 v21, v22, v23
	global_store_dwordx2 v[46:47], v[20:21], off
	global_store_dwordx4 v[34:35], v[16:19], off
	s_nop 1
	v_cvt_pk_bf16_f32 v16, v16, v17
	v_cvt_pk_bf16_f32 v17, v18, v19
	global_store_dwordx2 v[32:33], v[16:17], off
	global_load_dword v28, v[132:133], off offset:704
	v_and_or_b32 v18, v130, s4, v81
	v_lshlrev_b64 v[16:17], 12, v[130:131]
	v_ashrrev_i32_e32 v19, 31, v18
	v_lshlrev_b64 v[18:19], 9, v[18:19]
	v_lshl_add_u64 v[16:17], s[2:3], 0, v[16:17]
	v_lshl_add_u64 v[20:21], v[16:17], 0, v[146:147]
	v_lshl_add_u64 v[18:19], s[0:1], 0, v[18:19]
	v_lshl_add_u64 v[26:27], v[18:19], 0, v[138:139]
	v_lshl_add_u64 v[22:23], v[16:17], 0, v[144:145]
	v_lshl_add_u64 v[24:25], v[16:17], 0, v[142:143]
	v_lshl_add_u64 v[30:31], v[18:19], 0, v[136:137]
	v_lshl_add_u64 v[16:17], v[16:17], 0, v[140:141]
	s_waitcnt vmcnt(0)
	v_fmac_f32_e32 v148, 0x3a800000, v28
	v_mul_f32_e32 v28, 0x4b800000, v148
	v_cmp_gt_f32_e32 vcc, s6, v148
	s_nop 1
	v_cndmask_b32_e32 v28, v148, v28, vcc
	v_rsq_f32_e32 v32, v28
	v_lshl_add_u64 v[28:29], v[18:19], 0, v[134:135]
	v_lshl_add_u64 v[18:19], v[18:19], 0, v[112:113]
	v_mul_f32_e32 v33, 0x45800000, v32
	v_cndmask_b32_e32 v32, v32, v33, vcc
	v_pk_mul_f32 v[14:15], v[14:15], v[32:33] op_sel_hi:[1,0]
	v_pk_mul_f32 v[12:13], v[12:13], v[32:33] op_sel_hi:[1,0]
	v_pk_mul_f32 v[8:9], v[8:9], v[32:33] op_sel_hi:[1,0]
	global_store_dwordx4 v[20:21], v[12:15], off
	v_pk_mul_f32 v[10:11], v[10:11], v[32:33] op_sel_hi:[1,0]
	v_pk_mul_f32 v[4:5], v[4:5], v[32:33] op_sel_hi:[1,0]
	v_cvt_pk_bf16_f32 v12, v12, v13
	v_cvt_pk_bf16_f32 v13, v14, v15
	global_store_dwordx2 v[26:27], v[12:13], off
	global_store_dwordx4 v[22:23], v[8:11], off
	v_pk_mul_f32 v[6:7], v[6:7], v[32:33] op_sel_hi:[1,0]
	v_pk_mul_f32 v[0:1], v[0:1], v[32:33] op_sel_hi:[1,0]
	v_cvt_pk_bf16_f32 v8, v8, v9
	v_cvt_pk_bf16_f32 v9, v10, v11
	global_store_dwordx2 v[28:29], v[8:9], off
	global_store_dwordx4 v[24:25], v[4:7], off
	v_pk_mul_f32 v[2:3], v[2:3], v[32:33] op_sel_hi:[1,0]
	s_nop 0
	v_cvt_pk_bf16_f32 v4, v4, v5
	v_cvt_pk_bf16_f32 v5, v6, v7
	global_store_dwordx2 v[30:31], v[4:5], off
	global_store_dwordx4 v[16:17], v[0:3], off
	s_nop 1
	v_cvt_pk_bf16_f32 v0, v0, v1
	v_cvt_pk_bf16_f32 v1, v2, v3
	global_store_dwordx2 v[18:19], v[0:1], off
	s_waitcnt vmcnt(0)
	s_cbranch_scc0 .LBB0_440
	s_barrier

.LBB0_990:
	ds_read_b128 v[146:149], v155
	ds_read_b128 v[160:163], v155 offset:1024
	ds_read_b128 v[164:167], v155 offset:2048
	ds_read_b128 v[168:171], v155 offset:3072
	ds_read_b128 v[172:175], v156
	ds_read_b128 v[176:179], v156 offset:1024
	ds_read_b128 v[180:183], v156 offset:2048
	ds_read_b128 v[184:187], v156 offset:3072
	s_add_u32 s23, s54, 0xfffc0080
	s_addc_u32 s33, s55, -1
	s_cmp_eq_u32 s75, 12
	s_cselect_b32 s59, s20, s33
	s_cselect_b32 s58, s21, s23
	s_cselect_b32 s57, s19, s74
	s_cselect_b32 s56, s45, s73
	s_add_i32 m0, s51, 0xc000
	ds_read_b128 v[188:191], v157
	ds_read_b128 v[192:195], v157 offset:1024
	ds_read_b128 v[196:199], v157 offset:2048
	ds_read_b128 v[200:203], v157 offset:3072
	ds_read_b128 v[204:207], v157 offset:4096
	ds_read_b128 v[208:211], v157 offset:5120
	ds_read_b128 v[212:215], v157 offset:6144
	ds_read_b128 v[216:219], v157 offset:7168
	global_load_lds_dwordx4 v138, s[54:55]
	s_add_i32 m0, s51, 0xe000
	s_nop 0
	global_load_lds_dwordx4 v140, s[54:55]
	s_waitcnt vmcnt(8)
	s_waitcnt lgkmcnt(0)
	s_barrier
	s_setprio 1
	v_mfma_f32_16x16x32_bf16 v[124:127], v[146:149], v[188:191], v[124:127]
	v_mfma_f32_16x16x32_bf16 v[120:123], v[164:167], v[188:191], v[120:123]
	v_mfma_f32_16x16x32_bf16 v[108:111], v[146:149], v[196:199], v[108:111]
	v_mfma_f32_16x16x32_bf16 v[104:107], v[164:167], v[196:199], v[104:107]
	v_mfma_f32_16x16x32_bf16 v[92:95], v[146:149], v[204:207], v[92:95]
	v_mfma_f32_16x16x32_bf16 v[88:91], v[164:167], v[204:207], v[88:91]
	v_mfma_f32_16x16x32_bf16 v[76:79], v[146:149], v[212:215], v[76:79]
	v_mfma_f32_16x16x32_bf16 v[72:75], v[164:167], v[212:215], v[72:75]
	v_mfma_f32_16x16x32_bf16 v[124:127], v[160:163], v[192:195], v[124:127]
	v_mfma_f32_16x16x32_bf16 v[120:123], v[168:171], v[192:195], v[120:123]
	v_mfma_f32_16x16x32_bf16 v[108:111], v[160:163], v[200:203], v[108:111]
	v_mfma_f32_16x16x32_bf16 v[104:107], v[168:171], v[200:203], v[104:107]
	v_mfma_f32_16x16x32_bf16 v[92:95], v[160:163], v[208:211], v[92:95]
	v_mfma_f32_16x16x32_bf16 v[88:91], v[168:171], v[208:211], v[88:91]
	v_mfma_f32_16x16x32_bf16 v[76:79], v[160:163], v[216:219], v[76:79]
	v_mfma_f32_16x16x32_bf16 v[72:75], v[168:171], v[216:219], v[72:75]
	v_mfma_f32_16x16x32_bf16 v[116:119], v[172:175], v[188:191], v[116:119]
	v_mfma_f32_16x16x32_bf16 v[112:115], v[180:183], v[188:191], v[112:115]
	v_mfma_f32_16x16x32_bf16 v[100:103], v[172:175], v[196:199], v[100:103]
	v_mfma_f32_16x16x32_bf16 v[96:99], v[180:183], v[196:199], v[96:99]
	v_mfma_f32_16x16x32_bf16 v[84:87], v[172:175], v[204:207], v[84:87]
	v_mfma_f32_16x16x32_bf16 v[80:83], v[180:183], v[204:207], v[80:83]
	v_mfma_f32_16x16x32_bf16 v[68:71], v[172:175], v[212:215], v[68:71]
	v_mfma_f32_16x16x32_bf16 v[64:67], v[180:183], v[212:215], v[64:67]
	v_mfma_f32_16x16x32_bf16 v[116:119], v[176:179], v[192:195], v[116:119]
	v_mfma_f32_16x16x32_bf16 v[112:115], v[184:187], v[192:195], v[112:115]
	v_mfma_f32_16x16x32_bf16 v[100:103], v[176:179], v[200:203], v[100:103]
	v_mfma_f32_16x16x32_bf16 v[96:99], v[184:187], v[200:203], v[96:99]
	v_mfma_f32_16x16x32_bf16 v[84:87], v[176:179], v[208:211], v[84:87]
	v_mfma_f32_16x16x32_bf16 v[80:83], v[184:187], v[208:211], v[80:83]
	v_mfma_f32_16x16x32_bf16 v[68:71], v[176:179], v[216:219], v[68:71]
	v_mfma_f32_16x16x32_bf16 v[64:67], v[184:187], v[216:219], v[64:67]
	s_setprio 0
	s_barrier
	s_add_u32 s98, s56, s14
	s_addc_u32 s99, s57, s15
	s_add_u32 s100, s58, s14
	s_addc_u32 s101, s59, s15
	s_add_i32 s23, s71, s62
	s_mov_b32 m0, s23
	ds_read_b128 v[188:191], v157 offset:16384
	ds_read_b128 v[192:195], v157 offset:17408
	ds_read_b128 v[196:199], v157 offset:18432
	ds_read_b128 v[200:203], v157 offset:19456
	ds_read_b128 v[204:207], v157 offset:20480
	ds_read_b128 v[208:211], v157 offset:21504
	ds_read_b128 v[212:215], v157 offset:22528
	ds_read_b128 v[216:219], v157 offset:23552
	global_load_lds_dwordx4 v132, s[56:57]
	s_add_i32 m0, s23, 0x2000
	s_add_u32 s76, s56, 0x40000
	s_addc_u32 s77, s57, 0
	s_add_i32 s23, s72, s62
	global_load_lds_dwordx4 v136, s[56:57]
	s_mov_b32 m0, s23
	s_nop 0
	global_load_lds_dwordx4 v132, s[76:77]
	s_add_i32 m0, s23, 0x2000
	s_nop 0
	global_load_lds_dwordx4 v136, s[76:77]
	s_mov_b32 m0, s51
	s_nop 0
	global_load_lds_dwordx4 v130, s[58:59]
	s_mov_b32 m0, s53
	s_nop 0
	global_load_lds_dwordx4 v134, s[58:59]
	s_waitcnt vmcnt(8)
	s_waitcnt lgkmcnt(0)
	s_barrier
	s_setprio 1
	v_mfma_f32_16x16x32_bf16 v[60:63], v[146:149], v[188:191], v[60:63]
	v_mfma_f32_16x16x32_bf16 v[56:59], v[164:167], v[188:191], v[56:59]
	v_mfma_f32_16x16x32_bf16 v[44:47], v[146:149], v[196:199], v[44:47]
	v_mfma_f32_16x16x32_bf16 v[40:43], v[164:167], v[196:199], v[40:43]
	v_mfma_f32_16x16x32_bf16 v[28:31], v[146:149], v[204:207], v[28:31]
	v_mfma_f32_16x16x32_bf16 v[24:27], v[164:167], v[204:207], v[24:27]
	v_mfma_f32_16x16x32_bf16 v[12:15], v[146:149], v[212:215], v[12:15]
	v_mfma_f32_16x16x32_bf16 v[8:11], v[164:167], v[212:215], v[8:11]
	v_mfma_f32_16x16x32_bf16 v[60:63], v[160:163], v[192:195], v[60:63]
	v_mfma_f32_16x16x32_bf16 v[56:59], v[168:171], v[192:195], v[56:59]
	v_mfma_f32_16x16x32_bf16 v[44:47], v[160:163], v[200:203], v[44:47]
	v_mfma_f32_16x16x32_bf16 v[40:43], v[168:171], v[200:203], v[40:43]
	v_mfma_f32_16x16x32_bf16 v[28:31], v[160:163], v[208:211], v[28:31]
	v_mfma_f32_16x16x32_bf16 v[24:27], v[168:171], v[208:211], v[24:27]
	v_mfma_f32_16x16x32_bf16 v[12:15], v[160:163], v[216:219], v[12:15]
	v_mfma_f32_16x16x32_bf16 v[8:11], v[168:171], v[216:219], v[8:11]
	v_mfma_f32_16x16x32_bf16 v[52:55], v[172:175], v[188:191], v[52:55]
	v_mfma_f32_16x16x32_bf16 v[48:51], v[180:183], v[188:191], v[48:51]
	v_mfma_f32_16x16x32_bf16 v[36:39], v[172:175], v[196:199], v[36:39]
	v_mfma_f32_16x16x32_bf16 v[32:35], v[180:183], v[196:199], v[32:35]
	v_mfma_f32_16x16x32_bf16 v[20:23], v[172:175], v[204:207], v[20:23]
	v_mfma_f32_16x16x32_bf16 v[16:19], v[180:183], v[204:207], v[16:19]
	v_mfma_f32_16x16x32_bf16 v[4:7], v[172:175], v[212:215], v[4:7]
	v_mfma_f32_16x16x32_bf16 v[0:3], v[180:183], v[212:215], v[0:3]
	v_mfma_f32_16x16x32_bf16 v[52:55], v[176:179], v[192:195], v[52:55]
	v_mfma_f32_16x16x32_bf16 v[48:51], v[184:187], v[192:195], v[48:51]
	v_mfma_f32_16x16x32_bf16 v[36:39], v[176:179], v[200:203], v[36:39]
	v_mfma_f32_16x16x32_bf16 v[32:35], v[184:187], v[200:203], v[32:35]
	v_mfma_f32_16x16x32_bf16 v[20:23], v[176:179], v[208:211], v[20:23]
	v_mfma_f32_16x16x32_bf16 v[16:19], v[184:187], v[208:211], v[16:19]
	v_mfma_f32_16x16x32_bf16 v[4:7], v[176:179], v[216:219], v[4:7]
	v_mfma_f32_16x16x32_bf16 v[0:3], v[184:187], v[216:219], v[0:3]
	s_setprio 0
	s_barrier
	s_add_i32 s23, 0, 0x18000
	v_add_u32_e32 v159, s23, v153
	s_add_i32 s33, 0, 0x1c000
	ds_read_b128 v[146:149], v159
	ds_read_b128 v[160:163], v159 offset:1024
	ds_read_b128 v[164:167], v159 offset:2048
	ds_read_b128 v[168:171], v159 offset:3072
	v_add_u32_e32 v159, s33, v153
	ds_read_b128 v[172:175], v159
	ds_read_b128 v[176:179], v159 offset:1024
	ds_read_b128 v[180:183], v159 offset:2048
	ds_read_b128 v[184:187], v159 offset:3072
	s_add_u32 s58, s58, 0x40000
	s_addc_u32 s59, s59, 0
	s_mov_b32 m0, s63
	ds_read_b128 v[188:191], v157 offset:32768
	ds_read_b128 v[192:195], v157 offset:33792
	ds_read_b128 v[196:199], v157 offset:34816
	ds_read_b128 v[200:203], v157 offset:35840
	ds_read_b128 v[204:207], v157 offset:36864
	ds_read_b128 v[208:211], v157 offset:37888
	ds_read_b128 v[212:215], v157 offset:38912
	ds_read_b128 v[216:219], v157 offset:39936
	global_load_lds_dwordx4 v130, s[58:59]
	s_mov_b32 m0, s64
	s_nop 0
	global_load_lds_dwordx4 v134, s[58:59]
	s_waitcnt vmcnt(8)
	s_waitcnt lgkmcnt(0)
	s_barrier
	s_setprio 1
	v_mfma_f32_16x16x32_bf16 v[124:127], v[146:149], v[188:191], v[124:127]
	v_mfma_f32_16x16x32_bf16 v[120:123], v[164:167], v[188:191], v[120:123]
	v_mfma_f32_16x16x32_bf16 v[108:111], v[146:149], v[196:199], v[108:111]
	v_mfma_f32_16x16x32_bf16 v[104:107], v[164:167], v[196:199], v[104:107]
	v_mfma_f32_16x16x32_bf16 v[92:95], v[146:149], v[204:207], v[92:95]
	v_mfma_f32_16x16x32_bf16 v[88:91], v[164:167], v[204:207], v[88:91]
	v_mfma_f32_16x16x32_bf16 v[76:79], v[146:149], v[212:215], v[76:79]
	v_mfma_f32_16x16x32_bf16 v[72:75], v[164:167], v[212:215], v[72:75]
	v_mfma_f32_16x16x32_bf16 v[124:127], v[160:163], v[192:195], v[124:127]
	v_mfma_f32_16x16x32_bf16 v[120:123], v[168:171], v[192:195], v[120:123]
	v_mfma_f32_16x16x32_bf16 v[108:111], v[160:163], v[200:203], v[108:111]
	v_mfma_f32_16x16x32_bf16 v[104:107], v[168:171], v[200:203], v[104:107]
	v_mfma_f32_16x16x32_bf16 v[92:95], v[160:163], v[208:211], v[92:95]
	v_mfma_f32_16x16x32_bf16 v[88:91], v[168:171], v[208:211], v[88:91]
	v_mfma_f32_16x16x32_bf16 v[76:79], v[160:163], v[216:219], v[76:79]
	v_mfma_f32_16x16x32_bf16 v[72:75], v[168:171], v[216:219], v[72:75]
	v_mfma_f32_16x16x32_bf16 v[116:119], v[172:175], v[188:191], v[116:119]
	v_mfma_f32_16x16x32_bf16 v[112:115], v[180:183], v[188:191], v[112:115]
	v_mfma_f32_16x16x32_bf16 v[100:103], v[172:175], v[196:199], v[100:103]
	v_mfma_f32_16x16x32_bf16 v[96:99], v[180:183], v[196:199], v[96:99]
	v_mfma_f32_16x16x32_bf16 v[84:87], v[172:175], v[204:207], v[84:87]
	v_mfma_f32_16x16x32_bf16 v[80:83], v[180:183], v[204:207], v[80:83]
	v_mfma_f32_16x16x32_bf16 v[68:71], v[172:175], v[212:215], v[68:71]
	v_mfma_f32_16x16x32_bf16 v[64:67], v[180:183], v[212:215], v[64:67]
	v_mfma_f32_16x16x32_bf16 v[116:119], v[176:179], v[192:195], v[116:119]
	v_mfma_f32_16x16x32_bf16 v[112:115], v[184:187], v[192:195], v[112:115]
	v_mfma_f32_16x16x32_bf16 v[100:103], v[176:179], v[200:203], v[100:103]
	v_mfma_f32_16x16x32_bf16 v[96:99], v[184:187], v[200:203], v[96:99]
	v_mfma_f32_16x16x32_bf16 v[84:87], v[176:179], v[208:211], v[84:87]
	v_mfma_f32_16x16x32_bf16 v[80:83], v[184:187], v[208:211], v[80:83]
	v_mfma_f32_16x16x32_bf16 v[68:71], v[176:179], v[216:219], v[68:71]
	v_mfma_f32_16x16x32_bf16 v[64:67], v[184:187], v[216:219], v[64:67]
	s_setprio 0
	s_barrier
	s_add_i32 s23, s23, s62
	s_mov_b32 m0, s23
	ds_read_b128 v[188:191], v157 offset:49152
	ds_read_b128 v[192:195], v157 offset:50176
	ds_read_b128 v[196:199], v157 offset:51200
	ds_read_b128 v[200:203], v157 offset:52224
	ds_read_b128 v[204:207], v157 offset:53248
	ds_read_b128 v[208:211], v157 offset:54272
	ds_read_b128 v[212:215], v157 offset:55296
	ds_read_b128 v[216:219], v157 offset:56320
	global_load_lds_dwordx4 v132, s[98:99]
	s_add_i32 m0, s23, 0x2000
	s_add_u32 s56, s56, 0x40080
	s_addc_u32 s57, s57, 0
	s_add_i32 s23, s33, s62
	global_load_lds_dwordx4 v136, s[98:99]
	s_mov_b32 m0, s23
	s_nop 0
	global_load_lds_dwordx4 v132, s[56:57]
	s_add_i32 m0, s23, 0x2000
	s_nop 0
	global_load_lds_dwordx4 v136, s[56:57]
	s_mov_b32 m0, s68
	s_nop 0
	global_load_lds_dwordx4 v130, s[100:101]
	s_mov_b32 m0, s69
	s_nop 0
	global_load_lds_dwordx4 v134, s[100:101]
	s_waitcnt vmcnt(8)
	s_waitcnt lgkmcnt(0)
	s_barrier
	s_setprio 1
	v_mfma_f32_16x16x32_bf16 v[60:63], v[146:149], v[188:191], v[60:63]
	v_mfma_f32_16x16x32_bf16 v[56:59], v[164:167], v[188:191], v[56:59]
	v_mfma_f32_16x16x32_bf16 v[44:47], v[146:149], v[196:199], v[44:47]
	v_mfma_f32_16x16x32_bf16 v[40:43], v[164:167], v[196:199], v[40:43]
	v_mfma_f32_16x16x32_bf16 v[28:31], v[146:149], v[204:207], v[28:31]
	v_mfma_f32_16x16x32_bf16 v[24:27], v[164:167], v[204:207], v[24:27]
	v_mfma_f32_16x16x32_bf16 v[12:15], v[146:149], v[212:215], v[12:15]
	v_mfma_f32_16x16x32_bf16 v[8:11], v[164:167], v[212:215], v[8:11]
	v_mfma_f32_16x16x32_bf16 v[60:63], v[160:163], v[192:195], v[60:63]
	v_mfma_f32_16x16x32_bf16 v[56:59], v[168:171], v[192:195], v[56:59]
	v_mfma_f32_16x16x32_bf16 v[44:47], v[160:163], v[200:203], v[44:47]
	v_mfma_f32_16x16x32_bf16 v[40:43], v[168:171], v[200:203], v[40:43]
	v_mfma_f32_16x16x32_bf16 v[28:31], v[160:163], v[208:211], v[28:31]
	v_mfma_f32_16x16x32_bf16 v[24:27], v[168:171], v[208:211], v[24:27]
	v_mfma_f32_16x16x32_bf16 v[12:15], v[160:163], v[216:219], v[12:15]
	v_mfma_f32_16x16x32_bf16 v[8:11], v[168:171], v[216:219], v[8:11]
	v_mfma_f32_16x16x32_bf16 v[52:55], v[172:175], v[188:191], v[52:55]
	v_mfma_f32_16x16x32_bf16 v[48:51], v[180:183], v[188:191], v[48:51]
	v_mfma_f32_16x16x32_bf16 v[36:39], v[172:175], v[196:199], v[36:39]
	v_mfma_f32_16x16x32_bf16 v[32:35], v[180:183], v[196:199], v[32:35]
	v_mfma_f32_16x16x32_bf16 v[20:23], v[172:175], v[204:207], v[20:23]
	v_mfma_f32_16x16x32_bf16 v[16:19], v[180:183], v[204:207], v[16:19]
	v_mfma_f32_16x16x32_bf16 v[4:7], v[172:175], v[212:215], v[4:7]
	v_mfma_f32_16x16x32_bf16 v[0:3], v[180:183], v[212:215], v[0:3]
	v_mfma_f32_16x16x32_bf16 v[52:55], v[176:179], v[192:195], v[52:55]
	v_mfma_f32_16x16x32_bf16 v[48:51], v[184:187], v[192:195], v[48:51]
	v_mfma_f32_16x16x32_bf16 v[36:39], v[176:179], v[200:203], v[36:39]
	v_mfma_f32_16x16x32_bf16 v[32:35], v[184:187], v[200:203], v[32:35]
	v_mfma_f32_16x16x32_bf16 v[20:23], v[176:179], v[208:211], v[20:23]
	v_mfma_f32_16x16x32_bf16 v[16:19], v[184:187], v[208:211], v[16:19]
	v_mfma_f32_16x16x32_bf16 v[4:7], v[176:179], v[216:219], v[4:7]
	v_mfma_f32_16x16x32_bf16 v[0:3], v[184:187], v[216:219], v[0:3]
	s_setprio 0
	s_barrier
	s_add_i32 s75, s75, 2
	s_add_u32 s54, s54, 0x100
	s_addc_u32 s55, s55, 0
	s_add_u32 s73, s73, 0x100
	s_addc_u32 s74, s74, 0
	s_cmp_gt_u32 s75, 13
	s_cbranch_scc0 .LBB0_990
	s_and_b64 vcc, exec, s[16:17]
	s_cbranch_vccz .LBB0_993
	s_barrier

.LBB0_1086:
	ds_read_b128 v[146:149], v155
	ds_read_b128 v[160:163], v155 offset:1024
	ds_read_b128 v[164:167], v155 offset:2048
	ds_read_b128 v[168:171], v155 offset:3072
	ds_read_b128 v[172:175], v156
	ds_read_b128 v[176:179], v156 offset:1024
	ds_read_b128 v[180:183], v156 offset:2048
	ds_read_b128 v[184:187], v156 offset:3072
	s_add_u32 s23, s54, 0xfffc0080
	s_addc_u32 s33, s55, -1
	s_cmp_eq_u32 s82, 12
	s_cselect_b32 s59, s20, s33
	s_cselect_b32 s58, s21, s23
	s_cselect_b32 s57, s47, s81
	s_cselect_b32 s56, s49, s80
	s_add_i32 m0, s64, 0xc000
	ds_read_b128 v[188:191], v157
	ds_read_b128 v[192:195], v157 offset:1024
	ds_read_b128 v[196:199], v157 offset:2048
	ds_read_b128 v[200:203], v157 offset:3072
	ds_read_b128 v[204:207], v157 offset:4096
	ds_read_b128 v[208:211], v157 offset:5120
	ds_read_b128 v[212:215], v157 offset:6144
	ds_read_b128 v[216:219], v157 offset:7168
	global_load_lds_dwordx4 v138, s[54:55]
	s_add_i32 m0, s64, 0xe000
	s_nop 0
	global_load_lds_dwordx4 v140, s[54:55]
	s_waitcnt vmcnt(8)
	s_waitcnt lgkmcnt(0)
	s_barrier
	s_setprio 1
	v_mfma_f32_16x16x32_bf16 v[124:127], v[146:149], v[188:191], v[124:127]
	v_mfma_f32_16x16x32_bf16 v[120:123], v[164:167], v[188:191], v[120:123]
	v_mfma_f32_16x16x32_bf16 v[108:111], v[146:149], v[196:199], v[108:111]
	v_mfma_f32_16x16x32_bf16 v[104:107], v[164:167], v[196:199], v[104:107]
	v_mfma_f32_16x16x32_bf16 v[92:95], v[146:149], v[204:207], v[92:95]
	v_mfma_f32_16x16x32_bf16 v[88:91], v[164:167], v[204:207], v[88:91]
	v_mfma_f32_16x16x32_bf16 v[76:79], v[146:149], v[212:215], v[76:79]
	v_mfma_f32_16x16x32_bf16 v[72:75], v[164:167], v[212:215], v[72:75]
	v_mfma_f32_16x16x32_bf16 v[124:127], v[160:163], v[192:195], v[124:127]
	v_mfma_f32_16x16x32_bf16 v[120:123], v[168:171], v[192:195], v[120:123]
	v_mfma_f32_16x16x32_bf16 v[108:111], v[160:163], v[200:203], v[108:111]
	v_mfma_f32_16x16x32_bf16 v[104:107], v[168:171], v[200:203], v[104:107]
	v_mfma_f32_16x16x32_bf16 v[92:95], v[160:163], v[208:211], v[92:95]
	v_mfma_f32_16x16x32_bf16 v[88:91], v[168:171], v[208:211], v[88:91]
	v_mfma_f32_16x16x32_bf16 v[76:79], v[160:163], v[216:219], v[76:79]
	v_mfma_f32_16x16x32_bf16 v[72:75], v[168:171], v[216:219], v[72:75]
	v_mfma_f32_16x16x32_bf16 v[116:119], v[172:175], v[188:191], v[116:119]
	v_mfma_f32_16x16x32_bf16 v[112:115], v[180:183], v[188:191], v[112:115]
	v_mfma_f32_16x16x32_bf16 v[100:103], v[172:175], v[196:199], v[100:103]
	v_mfma_f32_16x16x32_bf16 v[96:99], v[180:183], v[196:199], v[96:99]
	v_mfma_f32_16x16x32_bf16 v[84:87], v[172:175], v[204:207], v[84:87]
	v_mfma_f32_16x16x32_bf16 v[80:83], v[180:183], v[204:207], v[80:83]
	v_mfma_f32_16x16x32_bf16 v[68:71], v[172:175], v[212:215], v[68:71]
	v_mfma_f32_16x16x32_bf16 v[64:67], v[180:183], v[212:215], v[64:67]
	v_mfma_f32_16x16x32_bf16 v[116:119], v[176:179], v[192:195], v[116:119]
	v_mfma_f32_16x16x32_bf16 v[112:115], v[184:187], v[192:195], v[112:115]
	v_mfma_f32_16x16x32_bf16 v[100:103], v[176:179], v[200:203], v[100:103]
	v_mfma_f32_16x16x32_bf16 v[96:99], v[184:187], v[200:203], v[96:99]
	v_mfma_f32_16x16x32_bf16 v[84:87], v[176:179], v[208:211], v[84:87]
	v_mfma_f32_16x16x32_bf16 v[80:83], v[184:187], v[208:211], v[80:83]
	v_mfma_f32_16x16x32_bf16 v[68:71], v[176:179], v[216:219], v[68:71]
	v_mfma_f32_16x16x32_bf16 v[64:67], v[184:187], v[216:219], v[64:67]
	s_setprio 0
	s_barrier
	s_add_u32 s98, s56, s16
	s_addc_u32 s99, s57, s17
	s_add_u32 s100, s58, s16
	s_addc_u32 s101, s59, s17
	s_add_i32 s23, s73, s62
	s_mov_b32 m0, s23
	ds_read_b128 v[188:191], v157 offset:16384
	ds_read_b128 v[192:195], v157 offset:17408
	ds_read_b128 v[196:199], v157 offset:18432
	ds_read_b128 v[200:203], v157 offset:19456
	ds_read_b128 v[204:207], v157 offset:20480
	ds_read_b128 v[208:211], v157 offset:21504
	ds_read_b128 v[212:215], v157 offset:22528
	ds_read_b128 v[216:219], v157 offset:23552
	global_load_lds_dwordx4 v132, s[56:57]
	s_add_i32 m0, s23, 0x2000
	s_add_u32 s84, s56, 0x40000
	s_addc_u32 s85, s57, 0
	s_add_i32 s23, s74, s62
	global_load_lds_dwordx4 v136, s[56:57]
	s_mov_b32 m0, s23
	s_nop 0
	global_load_lds_dwordx4 v132, s[84:85]
	s_add_i32 m0, s23, 0x2000
	s_nop 0
	global_load_lds_dwordx4 v136, s[84:85]
	s_mov_b32 m0, s64
	s_nop 0
	global_load_lds_dwordx4 v130, s[58:59]
	s_mov_b32 m0, s65
	s_nop 0
	global_load_lds_dwordx4 v134, s[58:59]
	s_waitcnt vmcnt(8)
	s_waitcnt lgkmcnt(0)
	s_barrier
	s_setprio 1
	v_mfma_f32_16x16x32_bf16 v[60:63], v[146:149], v[188:191], v[60:63]
	v_mfma_f32_16x16x32_bf16 v[56:59], v[164:167], v[188:191], v[56:59]
	v_mfma_f32_16x16x32_bf16 v[44:47], v[146:149], v[196:199], v[44:47]
	v_mfma_f32_16x16x32_bf16 v[40:43], v[164:167], v[196:199], v[40:43]
	v_mfma_f32_16x16x32_bf16 v[28:31], v[146:149], v[204:207], v[28:31]
	v_mfma_f32_16x16x32_bf16 v[24:27], v[164:167], v[204:207], v[24:27]
	v_mfma_f32_16x16x32_bf16 v[12:15], v[146:149], v[212:215], v[12:15]
	v_mfma_f32_16x16x32_bf16 v[8:11], v[164:167], v[212:215], v[8:11]
	v_mfma_f32_16x16x32_bf16 v[60:63], v[160:163], v[192:195], v[60:63]
	v_mfma_f32_16x16x32_bf16 v[56:59], v[168:171], v[192:195], v[56:59]
	v_mfma_f32_16x16x32_bf16 v[44:47], v[160:163], v[200:203], v[44:47]
	v_mfma_f32_16x16x32_bf16 v[40:43], v[168:171], v[200:203], v[40:43]
	v_mfma_f32_16x16x32_bf16 v[28:31], v[160:163], v[208:211], v[28:31]
	v_mfma_f32_16x16x32_bf16 v[24:27], v[168:171], v[208:211], v[24:27]
	v_mfma_f32_16x16x32_bf16 v[12:15], v[160:163], v[216:219], v[12:15]
	v_mfma_f32_16x16x32_bf16 v[8:11], v[168:171], v[216:219], v[8:11]
	v_mfma_f32_16x16x32_bf16 v[52:55], v[172:175], v[188:191], v[52:55]
	v_mfma_f32_16x16x32_bf16 v[48:51], v[180:183], v[188:191], v[48:51]
	v_mfma_f32_16x16x32_bf16 v[36:39], v[172:175], v[196:199], v[36:39]
	v_mfma_f32_16x16x32_bf16 v[32:35], v[180:183], v[196:199], v[32:35]
	v_mfma_f32_16x16x32_bf16 v[20:23], v[172:175], v[204:207], v[20:23]
	v_mfma_f32_16x16x32_bf16 v[16:19], v[180:183], v[204:207], v[16:19]
	v_mfma_f32_16x16x32_bf16 v[4:7], v[172:175], v[212:215], v[4:7]
	v_mfma_f32_16x16x32_bf16 v[0:3], v[180:183], v[212:215], v[0:3]
	v_mfma_f32_16x16x32_bf16 v[52:55], v[176:179], v[192:195], v[52:55]
	v_mfma_f32_16x16x32_bf16 v[48:51], v[184:187], v[192:195], v[48:51]
	v_mfma_f32_16x16x32_bf16 v[36:39], v[176:179], v[200:203], v[36:39]
	v_mfma_f32_16x16x32_bf16 v[32:35], v[184:187], v[200:203], v[32:35]
	v_mfma_f32_16x16x32_bf16 v[20:23], v[176:179], v[208:211], v[20:23]
	v_mfma_f32_16x16x32_bf16 v[16:19], v[184:187], v[208:211], v[16:19]
	v_mfma_f32_16x16x32_bf16 v[4:7], v[176:179], v[216:219], v[4:7]
	v_mfma_f32_16x16x32_bf16 v[0:3], v[184:187], v[216:219], v[0:3]
	s_setprio 0
	s_barrier
	s_add_i32 s23, 0, 0x18000
	v_add_u32_e32 v159, s23, v153
	s_add_i32 s33, 0, 0x1c000
	ds_read_b128 v[146:149], v159
	ds_read_b128 v[160:163], v159 offset:1024
	ds_read_b128 v[164:167], v159 offset:2048
	ds_read_b128 v[168:171], v159 offset:3072
	v_add_u32_e32 v159, s33, v153
	ds_read_b128 v[172:175], v159
	ds_read_b128 v[176:179], v159 offset:1024
	ds_read_b128 v[180:183], v159 offset:2048
	ds_read_b128 v[184:187], v159 offset:3072
	s_add_u32 s58, s58, 0x40000
	s_addc_u32 s59, s59, 0
	s_mov_b32 m0, s66
	ds_read_b128 v[188:191], v157 offset:32768
	ds_read_b128 v[192:195], v157 offset:33792
	ds_read_b128 v[196:199], v157 offset:34816
	ds_read_b128 v[200:203], v157 offset:35840
	ds_read_b128 v[204:207], v157 offset:36864
	ds_read_b128 v[208:211], v157 offset:37888
	ds_read_b128 v[212:215], v157 offset:38912
	ds_read_b128 v[216:219], v157 offset:39936
	global_load_lds_dwordx4 v130, s[58:59]
	s_mov_b32 m0, s67
	s_nop 0
	global_load_lds_dwordx4 v134, s[58:59]
	s_waitcnt vmcnt(8)
	s_waitcnt lgkmcnt(0)
	s_barrier
	s_setprio 1
	v_mfma_f32_16x16x32_bf16 v[124:127], v[146:149], v[188:191], v[124:127]
	v_mfma_f32_16x16x32_bf16 v[120:123], v[164:167], v[188:191], v[120:123]
	v_mfma_f32_16x16x32_bf16 v[108:111], v[146:149], v[196:199], v[108:111]
	v_mfma_f32_16x16x32_bf16 v[104:107], v[164:167], v[196:199], v[104:107]
	v_mfma_f32_16x16x32_bf16 v[92:95], v[146:149], v[204:207], v[92:95]
	v_mfma_f32_16x16x32_bf16 v[88:91], v[164:167], v[204:207], v[88:91]
	v_mfma_f32_16x16x32_bf16 v[76:79], v[146:149], v[212:215], v[76:79]
	v_mfma_f32_16x16x32_bf16 v[72:75], v[164:167], v[212:215], v[72:75]
	v_mfma_f32_16x16x32_bf16 v[124:127], v[160:163], v[192:195], v[124:127]
	v_mfma_f32_16x16x32_bf16 v[120:123], v[168:171], v[192:195], v[120:123]
	v_mfma_f32_16x16x32_bf16 v[108:111], v[160:163], v[200:203], v[108:111]
	v_mfma_f32_16x16x32_bf16 v[104:107], v[168:171], v[200:203], v[104:107]
	v_mfma_f32_16x16x32_bf16 v[92:95], v[160:163], v[208:211], v[92:95]
	v_mfma_f32_16x16x32_bf16 v[88:91], v[168:171], v[208:211], v[88:91]
	v_mfma_f32_16x16x32_bf16 v[76:79], v[160:163], v[216:219], v[76:79]
	v_mfma_f32_16x16x32_bf16 v[72:75], v[168:171], v[216:219], v[72:75]
	v_mfma_f32_16x16x32_bf16 v[116:119], v[172:175], v[188:191], v[116:119]
	v_mfma_f32_16x16x32_bf16 v[112:115], v[180:183], v[188:191], v[112:115]
	v_mfma_f32_16x16x32_bf16 v[100:103], v[172:175], v[196:199], v[100:103]
	v_mfma_f32_16x16x32_bf16 v[96:99], v[180:183], v[196:199], v[96:99]
	v_mfma_f32_16x16x32_bf16 v[84:87], v[172:175], v[204:207], v[84:87]
	v_mfma_f32_16x16x32_bf16 v[80:83], v[180:183], v[204:207], v[80:83]
	v_mfma_f32_16x16x32_bf16 v[68:71], v[172:175], v[212:215], v[68:71]
	v_mfma_f32_16x16x32_bf16 v[64:67], v[180:183], v[212:215], v[64:67]
	v_mfma_f32_16x16x32_bf16 v[116:119], v[176:179], v[192:195], v[116:119]
	v_mfma_f32_16x16x32_bf16 v[112:115], v[184:187], v[192:195], v[112:115]
	v_mfma_f32_16x16x32_bf16 v[100:103], v[176:179], v[200:203], v[100:103]
	v_mfma_f32_16x16x32_bf16 v[96:99], v[184:187], v[200:203], v[96:99]
	v_mfma_f32_16x16x32_bf16 v[84:87], v[176:179], v[208:211], v[84:87]
	v_mfma_f32_16x16x32_bf16 v[80:83], v[184:187], v[208:211], v[80:83]
	v_mfma_f32_16x16x32_bf16 v[68:71], v[176:179], v[216:219], v[68:71]
	v_mfma_f32_16x16x32_bf16 v[64:67], v[184:187], v[216:219], v[64:67]
	s_setprio 0
	s_barrier
	s_add_i32 s23, s23, s62
	s_mov_b32 m0, s23
	ds_read_b128 v[188:191], v157 offset:49152
	ds_read_b128 v[192:195], v157 offset:50176
	ds_read_b128 v[196:199], v157 offset:51200
	ds_read_b128 v[200:203], v157 offset:52224
	ds_read_b128 v[204:207], v157 offset:53248
	ds_read_b128 v[208:211], v157 offset:54272
	ds_read_b128 v[212:215], v157 offset:55296
	ds_read_b128 v[216:219], v157 offset:56320
	global_load_lds_dwordx4 v132, s[98:99]
	s_add_i32 m0, s23, 0x2000
	s_add_u32 s56, s56, 0x40080
	s_addc_u32 s57, s57, 0
	s_add_i32 s23, s33, s62
	global_load_lds_dwordx4 v136, s[98:99]
	s_mov_b32 m0, s23
	s_nop 0
	global_load_lds_dwordx4 v132, s[56:57]
	s_add_i32 m0, s23, 0x2000
	s_nop 0
	global_load_lds_dwordx4 v136, s[56:57]
	s_mov_b32 m0, s70
	s_nop 0
	global_load_lds_dwordx4 v130, s[100:101]
	s_mov_b32 m0, s71
	s_nop 0
	global_load_lds_dwordx4 v134, s[100:101]
	s_waitcnt vmcnt(8)
	s_waitcnt lgkmcnt(0)
	s_barrier
	s_setprio 1
	v_mfma_f32_16x16x32_bf16 v[60:63], v[146:149], v[188:191], v[60:63]
	v_mfma_f32_16x16x32_bf16 v[56:59], v[164:167], v[188:191], v[56:59]
	v_mfma_f32_16x16x32_bf16 v[44:47], v[146:149], v[196:199], v[44:47]
	v_mfma_f32_16x16x32_bf16 v[40:43], v[164:167], v[196:199], v[40:43]
	v_mfma_f32_16x16x32_bf16 v[28:31], v[146:149], v[204:207], v[28:31]
	v_mfma_f32_16x16x32_bf16 v[24:27], v[164:167], v[204:207], v[24:27]
	v_mfma_f32_16x16x32_bf16 v[12:15], v[146:149], v[212:215], v[12:15]
	v_mfma_f32_16x16x32_bf16 v[8:11], v[164:167], v[212:215], v[8:11]
	v_mfma_f32_16x16x32_bf16 v[60:63], v[160:163], v[192:195], v[60:63]
	v_mfma_f32_16x16x32_bf16 v[56:59], v[168:171], v[192:195], v[56:59]
	v_mfma_f32_16x16x32_bf16 v[44:47], v[160:163], v[200:203], v[44:47]
	v_mfma_f32_16x16x32_bf16 v[40:43], v[168:171], v[200:203], v[40:43]
	v_mfma_f32_16x16x32_bf16 v[28:31], v[160:163], v[208:211], v[28:31]
	v_mfma_f32_16x16x32_bf16 v[24:27], v[168:171], v[208:211], v[24:27]
	v_mfma_f32_16x16x32_bf16 v[12:15], v[160:163], v[216:219], v[12:15]
	v_mfma_f32_16x16x32_bf16 v[8:11], v[168:171], v[216:219], v[8:11]
	v_mfma_f32_16x16x32_bf16 v[52:55], v[172:175], v[188:191], v[52:55]
	v_mfma_f32_16x16x32_bf16 v[48:51], v[180:183], v[188:191], v[48:51]
	v_mfma_f32_16x16x32_bf16 v[36:39], v[172:175], v[196:199], v[36:39]
	v_mfma_f32_16x16x32_bf16 v[32:35], v[180:183], v[196:199], v[32:35]
	v_mfma_f32_16x16x32_bf16 v[20:23], v[172:175], v[204:207], v[20:23]
	v_mfma_f32_16x16x32_bf16 v[16:19], v[180:183], v[204:207], v[16:19]
	v_mfma_f32_16x16x32_bf16 v[4:7], v[172:175], v[212:215], v[4:7]
	v_mfma_f32_16x16x32_bf16 v[0:3], v[180:183], v[212:215], v[0:3]
	v_mfma_f32_16x16x32_bf16 v[52:55], v[176:179], v[192:195], v[52:55]
	v_mfma_f32_16x16x32_bf16 v[48:51], v[184:187], v[192:195], v[48:51]
	v_mfma_f32_16x16x32_bf16 v[36:39], v[176:179], v[200:203], v[36:39]
	v_mfma_f32_16x16x32_bf16 v[32:35], v[184:187], v[200:203], v[32:35]
	v_mfma_f32_16x16x32_bf16 v[20:23], v[176:179], v[208:211], v[20:23]
	v_mfma_f32_16x16x32_bf16 v[16:19], v[184:187], v[208:211], v[16:19]
	v_mfma_f32_16x16x32_bf16 v[4:7], v[176:179], v[216:219], v[4:7]
	v_mfma_f32_16x16x32_bf16 v[0:3], v[184:187], v[216:219], v[0:3]
	s_setprio 0
	s_barrier
	s_add_i32 s82, s82, 2
	s_add_u32 s54, s54, 0x100
	s_addc_u32 s55, s55, 0
	s_add_u32 s80, s80, 0x100
	s_addc_u32 s81, s81, 0
	s_cmp_gt_u32 s82, 13
	s_cbranch_scc0 .LBB0_1086
	s_and_b64 vcc, exec, s[18:19]
	s_cbranch_vccz .LBB0_1089
	s_barrier

.LBB0_1246:
	ds_read_b128 v[146:149], v155
	ds_read_b128 v[160:163], v155 offset:1024
	ds_read_b128 v[164:167], v155 offset:2048
	ds_read_b128 v[168:171], v155 offset:3072
	ds_read_b128 v[172:175], v156
	ds_read_b128 v[176:179], v156 offset:1024
	ds_read_b128 v[180:183], v156 offset:2048
	ds_read_b128 v[184:187], v156 offset:3072
	s_add_u32 s23, s46, 0xfffc0080
	s_addc_u32 s33, s47, -1
	s_cmp_eq_u32 s67, 12
	s_cselect_b32 s51, s20, s33
	s_cselect_b32 s50, s21, s23
	s_cselect_b32 s49, s19, s66
	s_cselect_b32 s48, s37, s65
	s_add_i32 m0, s43, 0xc000
	ds_read_b128 v[188:191], v157
	ds_read_b128 v[192:195], v157 offset:1024
	ds_read_b128 v[196:199], v157 offset:2048
	ds_read_b128 v[200:203], v157 offset:3072
	ds_read_b128 v[204:207], v157 offset:4096
	ds_read_b128 v[208:211], v157 offset:5120
	ds_read_b128 v[212:215], v157 offset:6144
	ds_read_b128 v[216:219], v157 offset:7168
	global_load_lds_dwordx4 v138, s[46:47]
	s_add_i32 m0, s43, 0xe000
	s_nop 0
	global_load_lds_dwordx4 v140, s[46:47]
	s_waitcnt vmcnt(8)
	s_waitcnt lgkmcnt(0)
	s_barrier
	s_setprio 1
	v_mfma_f32_16x16x32_bf16 v[124:127], v[146:149], v[188:191], v[124:127]
	v_mfma_f32_16x16x32_bf16 v[120:123], v[164:167], v[188:191], v[120:123]
	v_mfma_f32_16x16x32_bf16 v[108:111], v[146:149], v[196:199], v[108:111]
	v_mfma_f32_16x16x32_bf16 v[104:107], v[164:167], v[196:199], v[104:107]
	v_mfma_f32_16x16x32_bf16 v[92:95], v[146:149], v[204:207], v[92:95]
	v_mfma_f32_16x16x32_bf16 v[88:91], v[164:167], v[204:207], v[88:91]
	v_mfma_f32_16x16x32_bf16 v[76:79], v[146:149], v[212:215], v[76:79]
	v_mfma_f32_16x16x32_bf16 v[72:75], v[164:167], v[212:215], v[72:75]
	v_mfma_f32_16x16x32_bf16 v[124:127], v[160:163], v[192:195], v[124:127]
	v_mfma_f32_16x16x32_bf16 v[120:123], v[168:171], v[192:195], v[120:123]
	v_mfma_f32_16x16x32_bf16 v[108:111], v[160:163], v[200:203], v[108:111]
	v_mfma_f32_16x16x32_bf16 v[104:107], v[168:171], v[200:203], v[104:107]
	v_mfma_f32_16x16x32_bf16 v[92:95], v[160:163], v[208:211], v[92:95]
	v_mfma_f32_16x16x32_bf16 v[88:91], v[168:171], v[208:211], v[88:91]
	v_mfma_f32_16x16x32_bf16 v[76:79], v[160:163], v[216:219], v[76:79]
	v_mfma_f32_16x16x32_bf16 v[72:75], v[168:171], v[216:219], v[72:75]
	v_mfma_f32_16x16x32_bf16 v[116:119], v[172:175], v[188:191], v[116:119]
	v_mfma_f32_16x16x32_bf16 v[112:115], v[180:183], v[188:191], v[112:115]
	v_mfma_f32_16x16x32_bf16 v[100:103], v[172:175], v[196:199], v[100:103]
	v_mfma_f32_16x16x32_bf16 v[96:99], v[180:183], v[196:199], v[96:99]
	v_mfma_f32_16x16x32_bf16 v[84:87], v[172:175], v[204:207], v[84:87]
	v_mfma_f32_16x16x32_bf16 v[80:83], v[180:183], v[204:207], v[80:83]
	v_mfma_f32_16x16x32_bf16 v[68:71], v[172:175], v[212:215], v[68:71]
	v_mfma_f32_16x16x32_bf16 v[64:67], v[180:183], v[212:215], v[64:67]
	v_mfma_f32_16x16x32_bf16 v[116:119], v[176:179], v[192:195], v[116:119]
	v_mfma_f32_16x16x32_bf16 v[112:115], v[184:187], v[192:195], v[112:115]
	v_mfma_f32_16x16x32_bf16 v[100:103], v[176:179], v[200:203], v[100:103]
	v_mfma_f32_16x16x32_bf16 v[96:99], v[184:187], v[200:203], v[96:99]
	v_mfma_f32_16x16x32_bf16 v[84:87], v[176:179], v[208:211], v[84:87]
	v_mfma_f32_16x16x32_bf16 v[80:83], v[184:187], v[208:211], v[80:83]
	v_mfma_f32_16x16x32_bf16 v[68:71], v[176:179], v[216:219], v[68:71]
	v_mfma_f32_16x16x32_bf16 v[64:67], v[184:187], v[216:219], v[64:67]
	s_setprio 0
	s_barrier
	s_add_u32 s98, s48, s14
	s_addc_u32 s99, s49, s15
	s_add_u32 s100, s50, s14
	s_addc_u32 s101, s51, s15
	s_add_i32 s23, s63, s54
	s_mov_b32 m0, s23
	ds_read_b128 v[188:191], v157 offset:16384
	ds_read_b128 v[192:195], v157 offset:17408
	ds_read_b128 v[196:199], v157 offset:18432
	ds_read_b128 v[200:203], v157 offset:19456
	ds_read_b128 v[204:207], v157 offset:20480
	ds_read_b128 v[208:211], v157 offset:21504
	ds_read_b128 v[212:215], v157 offset:22528
	ds_read_b128 v[216:219], v157 offset:23552
	global_load_lds_dwordx4 v132, s[48:49]
	s_add_i32 m0, s23, 0x2000
	s_add_u32 s68, s48, 0x40000
	s_addc_u32 s69, s49, 0
	s_add_i32 s23, s64, s54
	global_load_lds_dwordx4 v136, s[48:49]
	s_mov_b32 m0, s23
	s_nop 0
	global_load_lds_dwordx4 v132, s[68:69]
	s_add_i32 m0, s23, 0x2000
	s_nop 0
	global_load_lds_dwordx4 v136, s[68:69]
	s_mov_b32 m0, s43
	s_nop 0
	global_load_lds_dwordx4 v130, s[50:51]
	s_mov_b32 m0, s45
	s_nop 0
	global_load_lds_dwordx4 v134, s[50:51]
	s_waitcnt vmcnt(8)
	s_waitcnt lgkmcnt(0)
	s_barrier
	s_setprio 1
	v_mfma_f32_16x16x32_bf16 v[60:63], v[146:149], v[188:191], v[60:63]
	v_mfma_f32_16x16x32_bf16 v[56:59], v[164:167], v[188:191], v[56:59]
	v_mfma_f32_16x16x32_bf16 v[44:47], v[146:149], v[196:199], v[44:47]
	v_mfma_f32_16x16x32_bf16 v[40:43], v[164:167], v[196:199], v[40:43]
	v_mfma_f32_16x16x32_bf16 v[28:31], v[146:149], v[204:207], v[28:31]
	v_mfma_f32_16x16x32_bf16 v[24:27], v[164:167], v[204:207], v[24:27]
	v_mfma_f32_16x16x32_bf16 v[12:15], v[146:149], v[212:215], v[12:15]
	v_mfma_f32_16x16x32_bf16 v[8:11], v[164:167], v[212:215], v[8:11]
	v_mfma_f32_16x16x32_bf16 v[60:63], v[160:163], v[192:195], v[60:63]
	v_mfma_f32_16x16x32_bf16 v[56:59], v[168:171], v[192:195], v[56:59]
	v_mfma_f32_16x16x32_bf16 v[44:47], v[160:163], v[200:203], v[44:47]
	v_mfma_f32_16x16x32_bf16 v[40:43], v[168:171], v[200:203], v[40:43]
	v_mfma_f32_16x16x32_bf16 v[28:31], v[160:163], v[208:211], v[28:31]
	v_mfma_f32_16x16x32_bf16 v[24:27], v[168:171], v[208:211], v[24:27]
	v_mfma_f32_16x16x32_bf16 v[12:15], v[160:163], v[216:219], v[12:15]
	v_mfma_f32_16x16x32_bf16 v[8:11], v[168:171], v[216:219], v[8:11]
	v_mfma_f32_16x16x32_bf16 v[52:55], v[172:175], v[188:191], v[52:55]
	v_mfma_f32_16x16x32_bf16 v[48:51], v[180:183], v[188:191], v[48:51]
	v_mfma_f32_16x16x32_bf16 v[36:39], v[172:175], v[196:199], v[36:39]
	v_mfma_f32_16x16x32_bf16 v[32:35], v[180:183], v[196:199], v[32:35]
	v_mfma_f32_16x16x32_bf16 v[20:23], v[172:175], v[204:207], v[20:23]
	v_mfma_f32_16x16x32_bf16 v[16:19], v[180:183], v[204:207], v[16:19]
	v_mfma_f32_16x16x32_bf16 v[4:7], v[172:175], v[212:215], v[4:7]
	v_mfma_f32_16x16x32_bf16 v[0:3], v[180:183], v[212:215], v[0:3]
	v_mfma_f32_16x16x32_bf16 v[52:55], v[176:179], v[192:195], v[52:55]
	v_mfma_f32_16x16x32_bf16 v[48:51], v[184:187], v[192:195], v[48:51]
	v_mfma_f32_16x16x32_bf16 v[36:39], v[176:179], v[200:203], v[36:39]
	v_mfma_f32_16x16x32_bf16 v[32:35], v[184:187], v[200:203], v[32:35]
	v_mfma_f32_16x16x32_bf16 v[20:23], v[176:179], v[208:211], v[20:23]
	v_mfma_f32_16x16x32_bf16 v[16:19], v[184:187], v[208:211], v[16:19]
	v_mfma_f32_16x16x32_bf16 v[4:7], v[176:179], v[216:219], v[4:7]
	v_mfma_f32_16x16x32_bf16 v[0:3], v[184:187], v[216:219], v[0:3]
	s_setprio 0
	s_barrier
	s_add_i32 s23, 0, 0x18000
	v_add_u32_e32 v159, s23, v153
	s_add_i32 s33, 0, 0x1c000
	ds_read_b128 v[146:149], v159
	ds_read_b128 v[160:163], v159 offset:1024
	ds_read_b128 v[164:167], v159 offset:2048
	ds_read_b128 v[168:171], v159 offset:3072
	v_add_u32_e32 v159, s33, v153
	ds_read_b128 v[172:175], v159
	ds_read_b128 v[176:179], v159 offset:1024
	ds_read_b128 v[180:183], v159 offset:2048
	ds_read_b128 v[184:187], v159 offset:3072
	s_add_u32 s50, s50, 0x40000
	s_addc_u32 s51, s51, 0
	s_mov_b32 m0, s55
	ds_read_b128 v[188:191], v157 offset:32768
	ds_read_b128 v[192:195], v157 offset:33792
	ds_read_b128 v[196:199], v157 offset:34816
	ds_read_b128 v[200:203], v157 offset:35840
	ds_read_b128 v[204:207], v157 offset:36864
	ds_read_b128 v[208:211], v157 offset:37888
	ds_read_b128 v[212:215], v157 offset:38912
	ds_read_b128 v[216:219], v157 offset:39936
	global_load_lds_dwordx4 v130, s[50:51]
	s_mov_b32 m0, s56
	s_nop 0
	global_load_lds_dwordx4 v134, s[50:51]
	s_waitcnt vmcnt(8)
	s_waitcnt lgkmcnt(0)
	s_barrier
	s_setprio 1
	v_mfma_f32_16x16x32_bf16 v[124:127], v[146:149], v[188:191], v[124:127]
	v_mfma_f32_16x16x32_bf16 v[120:123], v[164:167], v[188:191], v[120:123]
	v_mfma_f32_16x16x32_bf16 v[108:111], v[146:149], v[196:199], v[108:111]
	v_mfma_f32_16x16x32_bf16 v[104:107], v[164:167], v[196:199], v[104:107]
	v_mfma_f32_16x16x32_bf16 v[92:95], v[146:149], v[204:207], v[92:95]
	v_mfma_f32_16x16x32_bf16 v[88:91], v[164:167], v[204:207], v[88:91]
	v_mfma_f32_16x16x32_bf16 v[76:79], v[146:149], v[212:215], v[76:79]
	v_mfma_f32_16x16x32_bf16 v[72:75], v[164:167], v[212:215], v[72:75]
	v_mfma_f32_16x16x32_bf16 v[124:127], v[160:163], v[192:195], v[124:127]
	v_mfma_f32_16x16x32_bf16 v[120:123], v[168:171], v[192:195], v[120:123]
	v_mfma_f32_16x16x32_bf16 v[108:111], v[160:163], v[200:203], v[108:111]
	v_mfma_f32_16x16x32_bf16 v[104:107], v[168:171], v[200:203], v[104:107]
	v_mfma_f32_16x16x32_bf16 v[92:95], v[160:163], v[208:211], v[92:95]
	v_mfma_f32_16x16x32_bf16 v[88:91], v[168:171], v[208:211], v[88:91]
	v_mfma_f32_16x16x32_bf16 v[76:79], v[160:163], v[216:219], v[76:79]
	v_mfma_f32_16x16x32_bf16 v[72:75], v[168:171], v[216:219], v[72:75]
	v_mfma_f32_16x16x32_bf16 v[116:119], v[172:175], v[188:191], v[116:119]
	v_mfma_f32_16x16x32_bf16 v[112:115], v[180:183], v[188:191], v[112:115]
	v_mfma_f32_16x16x32_bf16 v[100:103], v[172:175], v[196:199], v[100:103]
	v_mfma_f32_16x16x32_bf16 v[96:99], v[180:183], v[196:199], v[96:99]
	v_mfma_f32_16x16x32_bf16 v[84:87], v[172:175], v[204:207], v[84:87]
	v_mfma_f32_16x16x32_bf16 v[80:83], v[180:183], v[204:207], v[80:83]
	v_mfma_f32_16x16x32_bf16 v[68:71], v[172:175], v[212:215], v[68:71]
	v_mfma_f32_16x16x32_bf16 v[64:67], v[180:183], v[212:215], v[64:67]
	v_mfma_f32_16x16x32_bf16 v[116:119], v[176:179], v[192:195], v[116:119]
	v_mfma_f32_16x16x32_bf16 v[112:115], v[184:187], v[192:195], v[112:115]
	v_mfma_f32_16x16x32_bf16 v[100:103], v[176:179], v[200:203], v[100:103]
	v_mfma_f32_16x16x32_bf16 v[96:99], v[184:187], v[200:203], v[96:99]
	v_mfma_f32_16x16x32_bf16 v[84:87], v[176:179], v[208:211], v[84:87]
	v_mfma_f32_16x16x32_bf16 v[80:83], v[184:187], v[208:211], v[80:83]
	v_mfma_f32_16x16x32_bf16 v[68:71], v[176:179], v[216:219], v[68:71]
	v_mfma_f32_16x16x32_bf16 v[64:67], v[184:187], v[216:219], v[64:67]
	s_setprio 0
	s_barrier
	s_add_i32 s23, s23, s54
	s_mov_b32 m0, s23
	ds_read_b128 v[188:191], v157 offset:49152
	ds_read_b128 v[192:195], v157 offset:50176
	ds_read_b128 v[196:199], v157 offset:51200
	ds_read_b128 v[200:203], v157 offset:52224
	ds_read_b128 v[204:207], v157 offset:53248
	ds_read_b128 v[208:211], v157 offset:54272
	ds_read_b128 v[212:215], v157 offset:55296
	ds_read_b128 v[216:219], v157 offset:56320
	global_load_lds_dwordx4 v132, s[98:99]
	s_add_i32 m0, s23, 0x2000
	s_add_u32 s48, s48, 0x40080
	s_addc_u32 s49, s49, 0
	s_add_i32 s23, s33, s54
	global_load_lds_dwordx4 v136, s[98:99]
	s_mov_b32 m0, s23
	s_nop 0
	global_load_lds_dwordx4 v132, s[48:49]
	s_add_i32 m0, s23, 0x2000
	s_nop 0
	global_load_lds_dwordx4 v136, s[48:49]
	s_mov_b32 m0, s60
	s_nop 0
	global_load_lds_dwordx4 v130, s[100:101]
	s_mov_b32 m0, s61
	s_nop 0
	global_load_lds_dwordx4 v134, s[100:101]
	s_waitcnt vmcnt(8)
	s_waitcnt lgkmcnt(0)
	s_barrier
	s_setprio 1
	v_mfma_f32_16x16x32_bf16 v[60:63], v[146:149], v[188:191], v[60:63]
	v_mfma_f32_16x16x32_bf16 v[56:59], v[164:167], v[188:191], v[56:59]
	v_mfma_f32_16x16x32_bf16 v[44:47], v[146:149], v[196:199], v[44:47]
	v_mfma_f32_16x16x32_bf16 v[40:43], v[164:167], v[196:199], v[40:43]
	v_mfma_f32_16x16x32_bf16 v[28:31], v[146:149], v[204:207], v[28:31]
	v_mfma_f32_16x16x32_bf16 v[24:27], v[164:167], v[204:207], v[24:27]
	v_mfma_f32_16x16x32_bf16 v[12:15], v[146:149], v[212:215], v[12:15]
	v_mfma_f32_16x16x32_bf16 v[8:11], v[164:167], v[212:215], v[8:11]
	v_mfma_f32_16x16x32_bf16 v[60:63], v[160:163], v[192:195], v[60:63]
	v_mfma_f32_16x16x32_bf16 v[56:59], v[168:171], v[192:195], v[56:59]
	v_mfma_f32_16x16x32_bf16 v[44:47], v[160:163], v[200:203], v[44:47]
	v_mfma_f32_16x16x32_bf16 v[40:43], v[168:171], v[200:203], v[40:43]
	v_mfma_f32_16x16x32_bf16 v[28:31], v[160:163], v[208:211], v[28:31]
	v_mfma_f32_16x16x32_bf16 v[24:27], v[168:171], v[208:211], v[24:27]
	v_mfma_f32_16x16x32_bf16 v[12:15], v[160:163], v[216:219], v[12:15]
	v_mfma_f32_16x16x32_bf16 v[8:11], v[168:171], v[216:219], v[8:11]
	v_mfma_f32_16x16x32_bf16 v[52:55], v[172:175], v[188:191], v[52:55]
	v_mfma_f32_16x16x32_bf16 v[48:51], v[180:183], v[188:191], v[48:51]
	v_mfma_f32_16x16x32_bf16 v[36:39], v[172:175], v[196:199], v[36:39]
	v_mfma_f32_16x16x32_bf16 v[32:35], v[180:183], v[196:199], v[32:35]
	v_mfma_f32_16x16x32_bf16 v[20:23], v[172:175], v[204:207], v[20:23]
	v_mfma_f32_16x16x32_bf16 v[16:19], v[180:183], v[204:207], v[16:19]
	v_mfma_f32_16x16x32_bf16 v[4:7], v[172:175], v[212:215], v[4:7]
	v_mfma_f32_16x16x32_bf16 v[0:3], v[180:183], v[212:215], v[0:3]
	v_mfma_f32_16x16x32_bf16 v[52:55], v[176:179], v[192:195], v[52:55]
	v_mfma_f32_16x16x32_bf16 v[48:51], v[184:187], v[192:195], v[48:51]
	v_mfma_f32_16x16x32_bf16 v[36:39], v[176:179], v[200:203], v[36:39]
	v_mfma_f32_16x16x32_bf16 v[32:35], v[184:187], v[200:203], v[32:35]
	v_mfma_f32_16x16x32_bf16 v[20:23], v[176:179], v[208:211], v[20:23]
	v_mfma_f32_16x16x32_bf16 v[16:19], v[184:187], v[208:211], v[16:19]
	v_mfma_f32_16x16x32_bf16 v[4:7], v[176:179], v[216:219], v[4:7]
	v_mfma_f32_16x16x32_bf16 v[0:3], v[184:187], v[216:219], v[0:3]
	s_setprio 0
	s_barrier
	s_add_i32 s67, s67, 2
	s_add_u32 s46, s46, 0x100
	s_addc_u32 s47, s47, 0
	s_add_u32 s65, s65, 0x100
	s_addc_u32 s66, s66, 0
	s_cmp_gt_u32 s67, 13
	s_cbranch_scc0 .LBB0_1246
	s_and_b64 vcc, exec, s[16:17]
	s_cbranch_vccz .LBB0_1249
	s_barrier

.LBB0_1342:
	ds_read_b128 v[146:149], v154
	ds_read_b128 v[158:161], v154 offset:1024
	ds_read_b128 v[162:165], v154 offset:2048
	ds_read_b128 v[166:169], v154 offset:3072
	ds_read_b128 v[170:173], v155
	ds_read_b128 v[174:177], v155 offset:1024
	ds_read_b128 v[178:181], v155 offset:2048
	ds_read_b128 v[182:185], v155 offset:3072
	s_add_u32 s23, s40, 0xfffc0080
	s_addc_u32 s33, s41, -1
	s_cmp_eq_u32 s67, 12
	s_cselect_b32 s45, s19, s33
	s_cselect_b32 s44, s20, s23
	s_cselect_b32 s43, s17, s66
	s_cselect_b32 s42, s21, s65
	s_add_i32 m0, s52, 0xc000
	ds_read_b128 v[186:189], v156
	ds_read_b128 v[190:193], v156 offset:1024
	ds_read_b128 v[194:197], v156 offset:2048
	ds_read_b128 v[198:201], v156 offset:3072
	ds_read_b128 v[202:205], v156 offset:4096
	ds_read_b128 v[206:209], v156 offset:5120
	ds_read_b128 v[210:213], v156 offset:6144
	ds_read_b128 v[214:217], v156 offset:7168
	global_load_lds_dwordx4 v138, s[40:41]
	s_add_i32 m0, s52, 0xe000
	s_nop 0
	global_load_lds_dwordx4 v140, s[40:41]
	s_waitcnt vmcnt(8)
	s_waitcnt lgkmcnt(0)
	s_barrier
	s_setprio 1
	v_mfma_f32_16x16x32_bf16 v[116:119], v[146:149], v[186:189], v[116:119]
	v_mfma_f32_16x16x32_bf16 v[112:115], v[162:165], v[186:189], v[112:115]
	v_mfma_f32_16x16x32_bf16 v[100:103], v[146:149], v[194:197], v[100:103]
	v_mfma_f32_16x16x32_bf16 v[96:99], v[162:165], v[194:197], v[96:99]
	v_mfma_f32_16x16x32_bf16 v[84:87], v[146:149], v[202:205], v[84:87]
	v_mfma_f32_16x16x32_bf16 v[80:83], v[162:165], v[202:205], v[80:83]
	v_mfma_f32_16x16x32_bf16 v[72:75], v[146:149], v[210:213], v[72:75]
	v_mfma_f32_16x16x32_bf16 v[64:67], v[162:165], v[210:213], v[64:67]
	v_mfma_f32_16x16x32_bf16 v[116:119], v[158:161], v[190:193], v[116:119]
	v_mfma_f32_16x16x32_bf16 v[112:115], v[166:169], v[190:193], v[112:115]
	v_mfma_f32_16x16x32_bf16 v[100:103], v[158:161], v[198:201], v[100:103]
	v_mfma_f32_16x16x32_bf16 v[96:99], v[166:169], v[198:201], v[96:99]
	v_mfma_f32_16x16x32_bf16 v[84:87], v[158:161], v[206:209], v[84:87]
	v_mfma_f32_16x16x32_bf16 v[80:83], v[166:169], v[206:209], v[80:83]
	v_mfma_f32_16x16x32_bf16 v[72:75], v[158:161], v[214:217], v[72:75]
	v_mfma_f32_16x16x32_bf16 v[64:67], v[166:169], v[214:217], v[64:67]
	v_mfma_f32_16x16x32_bf16 v[124:127], v[170:173], v[186:189], v[124:127]
	v_mfma_f32_16x16x32_bf16 v[120:123], v[178:181], v[186:189], v[120:123]
	v_mfma_f32_16x16x32_bf16 v[108:111], v[170:173], v[194:197], v[108:111]
	v_mfma_f32_16x16x32_bf16 v[104:107], v[178:181], v[194:197], v[104:107]
	v_mfma_f32_16x16x32_bf16 v[92:95], v[170:173], v[202:205], v[92:95]
	v_mfma_f32_16x16x32_bf16 v[88:91], v[178:181], v[202:205], v[88:91]
	v_mfma_f32_16x16x32_bf16 v[76:79], v[170:173], v[210:213], v[76:79]
	v_mfma_f32_16x16x32_bf16 v[68:71], v[178:181], v[210:213], v[68:71]
	v_mfma_f32_16x16x32_bf16 v[124:127], v[174:177], v[190:193], v[124:127]
	v_mfma_f32_16x16x32_bf16 v[120:123], v[182:185], v[190:193], v[120:123]
	v_mfma_f32_16x16x32_bf16 v[108:111], v[174:177], v[198:201], v[108:111]
	v_mfma_f32_16x16x32_bf16 v[104:107], v[182:185], v[198:201], v[104:107]
	v_mfma_f32_16x16x32_bf16 v[92:95], v[174:177], v[206:209], v[92:95]
	v_mfma_f32_16x16x32_bf16 v[88:91], v[182:185], v[206:209], v[88:91]
	v_mfma_f32_16x16x32_bf16 v[76:79], v[174:177], v[214:217], v[76:79]
	v_mfma_f32_16x16x32_bf16 v[68:71], v[182:185], v[214:217], v[68:71]
	s_setprio 0
	s_barrier
	s_add_u32 s98, s42, s12
	s_addc_u32 s99, s43, s13
	s_add_u32 s100, s44, s12
	s_addc_u32 s101, s45, s13
	s_add_i32 s23, s61, s50
	s_mov_b32 m0, s23
	ds_read_b128 v[186:189], v156 offset:16384
	ds_read_b128 v[190:193], v156 offset:17408
	ds_read_b128 v[194:197], v156 offset:18432
	ds_read_b128 v[198:201], v156 offset:19456
	ds_read_b128 v[202:205], v156 offset:20480
	ds_read_b128 v[206:209], v156 offset:21504
	ds_read_b128 v[210:213], v156 offset:22528
	ds_read_b128 v[214:217], v156 offset:23552
	global_load_lds_dwordx4 v132, s[42:43]
	s_add_i32 m0, s23, 0x2000
	s_add_u32 s68, s42, 0x40000
	s_addc_u32 s69, s43, 0
	s_add_i32 s23, s62, s50
	global_load_lds_dwordx4 v136, s[42:43]
	s_mov_b32 m0, s23
	s_nop 0
	global_load_lds_dwordx4 v132, s[68:69]
	s_add_i32 m0, s23, 0x2000
	s_nop 0
	global_load_lds_dwordx4 v136, s[68:69]
	s_mov_b32 m0, s52
	s_nop 0
	global_load_lds_dwordx4 v130, s[44:45]
	s_mov_b32 m0, s53
	s_nop 0
	global_load_lds_dwordx4 v134, s[44:45]
	s_waitcnt vmcnt(8)
	s_waitcnt lgkmcnt(0)
	s_barrier
	s_setprio 1
	v_mfma_f32_16x16x32_bf16 v[56:59], v[146:149], v[186:189], v[56:59]
	v_mfma_f32_16x16x32_bf16 v[48:51], v[162:165], v[186:189], v[48:51]
	v_mfma_f32_16x16x32_bf16 v[40:43], v[146:149], v[194:197], v[40:43]
	v_mfma_f32_16x16x32_bf16 v[32:35], v[162:165], v[194:197], v[32:35]
	v_mfma_f32_16x16x32_bf16 v[24:27], v[146:149], v[202:205], v[24:27]
	v_mfma_f32_16x16x32_bf16 v[16:19], v[162:165], v[202:205], v[16:19]
	v_mfma_f32_16x16x32_bf16 v[8:11], v[146:149], v[210:213], v[8:11]
	v_mfma_f32_16x16x32_bf16 v[0:3], v[162:165], v[210:213], v[0:3]
	v_mfma_f32_16x16x32_bf16 v[56:59], v[158:161], v[190:193], v[56:59]
	v_mfma_f32_16x16x32_bf16 v[48:51], v[166:169], v[190:193], v[48:51]
	v_mfma_f32_16x16x32_bf16 v[40:43], v[158:161], v[198:201], v[40:43]
	v_mfma_f32_16x16x32_bf16 v[32:35], v[166:169], v[198:201], v[32:35]
	v_mfma_f32_16x16x32_bf16 v[24:27], v[158:161], v[206:209], v[24:27]
	v_mfma_f32_16x16x32_bf16 v[16:19], v[166:169], v[206:209], v[16:19]
	v_mfma_f32_16x16x32_bf16 v[8:11], v[158:161], v[214:217], v[8:11]
	v_mfma_f32_16x16x32_bf16 v[0:3], v[166:169], v[214:217], v[0:3]
	v_mfma_f32_16x16x32_bf16 v[60:63], v[170:173], v[186:189], v[60:63]
	v_mfma_f32_16x16x32_bf16 v[52:55], v[178:181], v[186:189], v[52:55]
	v_mfma_f32_16x16x32_bf16 v[44:47], v[170:173], v[194:197], v[44:47]
	v_mfma_f32_16x16x32_bf16 v[36:39], v[178:181], v[194:197], v[36:39]
	v_mfma_f32_16x16x32_bf16 v[28:31], v[170:173], v[202:205], v[28:31]
	v_mfma_f32_16x16x32_bf16 v[20:23], v[178:181], v[202:205], v[20:23]
	v_mfma_f32_16x16x32_bf16 v[12:15], v[170:173], v[210:213], v[12:15]
	v_mfma_f32_16x16x32_bf16 v[4:7], v[178:181], v[210:213], v[4:7]
	v_mfma_f32_16x16x32_bf16 v[60:63], v[174:177], v[190:193], v[60:63]
	v_mfma_f32_16x16x32_bf16 v[52:55], v[182:185], v[190:193], v[52:55]
	v_mfma_f32_16x16x32_bf16 v[44:47], v[174:177], v[198:201], v[44:47]
	v_mfma_f32_16x16x32_bf16 v[36:39], v[182:185], v[198:201], v[36:39]
	v_mfma_f32_16x16x32_bf16 v[28:31], v[174:177], v[206:209], v[28:31]
	v_mfma_f32_16x16x32_bf16 v[20:23], v[182:185], v[206:209], v[20:23]
	v_mfma_f32_16x16x32_bf16 v[12:15], v[174:177], v[214:217], v[12:15]
	v_mfma_f32_16x16x32_bf16 v[4:7], v[182:185], v[214:217], v[4:7]
	s_setprio 0
	s_barrier
	s_add_i32 s23, 0, 0x18000
	s_add_i32 s33, 0, 0x1c000
	v_add_u32_e32 v166, s23, v152
	v_add_u32_e32 v182, s33, v152
	ds_read_b128 v[146:149], v166
	ds_read_b128 v[158:161], v166 offset:1024
	ds_read_b128 v[162:165], v166 offset:2048
	ds_read_b128 v[166:169], v166 offset:3072
	ds_read_b128 v[170:173], v182
	ds_read_b128 v[174:177], v182 offset:1024
	ds_read_b128 v[178:181], v182 offset:2048
	ds_read_b128 v[182:185], v182 offset:3072
	s_add_u32 s44, s44, 0x40000
	s_addc_u32 s45, s45, 0
	s_mov_b32 m0, s54
	ds_read_b128 v[186:189], v156 offset:32768
	ds_read_b128 v[190:193], v156 offset:33792
	ds_read_b128 v[194:197], v156 offset:34816
	ds_read_b128 v[198:201], v156 offset:35840
	ds_read_b128 v[202:205], v156 offset:36864
	ds_read_b128 v[206:209], v156 offset:37888
	ds_read_b128 v[210:213], v156 offset:38912
	ds_read_b128 v[214:217], v156 offset:39936
	global_load_lds_dwordx4 v130, s[44:45]
	s_mov_b32 m0, s55
	s_nop 0
	global_load_lds_dwordx4 v134, s[44:45]
	s_waitcnt vmcnt(8)
	s_waitcnt lgkmcnt(0)
	s_barrier
	s_setprio 1
	v_mfma_f32_16x16x32_bf16 v[116:119], v[146:149], v[186:189], v[116:119]
	v_mfma_f32_16x16x32_bf16 v[112:115], v[162:165], v[186:189], v[112:115]
	v_mfma_f32_16x16x32_bf16 v[100:103], v[146:149], v[194:197], v[100:103]
	v_mfma_f32_16x16x32_bf16 v[96:99], v[162:165], v[194:197], v[96:99]
	v_mfma_f32_16x16x32_bf16 v[84:87], v[146:149], v[202:205], v[84:87]
	v_mfma_f32_16x16x32_bf16 v[80:83], v[162:165], v[202:205], v[80:83]
	v_mfma_f32_16x16x32_bf16 v[72:75], v[146:149], v[210:213], v[72:75]
	v_mfma_f32_16x16x32_bf16 v[64:67], v[162:165], v[210:213], v[64:67]
	v_mfma_f32_16x16x32_bf16 v[116:119], v[158:161], v[190:193], v[116:119]
	v_mfma_f32_16x16x32_bf16 v[112:115], v[166:169], v[190:193], v[112:115]
	v_mfma_f32_16x16x32_bf16 v[100:103], v[158:161], v[198:201], v[100:103]
	v_mfma_f32_16x16x32_bf16 v[96:99], v[166:169], v[198:201], v[96:99]
	v_mfma_f32_16x16x32_bf16 v[84:87], v[158:161], v[206:209], v[84:87]
	v_mfma_f32_16x16x32_bf16 v[80:83], v[166:169], v[206:209], v[80:83]
	v_mfma_f32_16x16x32_bf16 v[72:75], v[158:161], v[214:217], v[72:75]
	v_mfma_f32_16x16x32_bf16 v[64:67], v[166:169], v[214:217], v[64:67]
	v_mfma_f32_16x16x32_bf16 v[124:127], v[170:173], v[186:189], v[124:127]
	v_mfma_f32_16x16x32_bf16 v[120:123], v[178:181], v[186:189], v[120:123]
	v_mfma_f32_16x16x32_bf16 v[108:111], v[170:173], v[194:197], v[108:111]
	v_mfma_f32_16x16x32_bf16 v[104:107], v[178:181], v[194:197], v[104:107]
	v_mfma_f32_16x16x32_bf16 v[92:95], v[170:173], v[202:205], v[92:95]
	v_mfma_f32_16x16x32_bf16 v[88:91], v[178:181], v[202:205], v[88:91]
	v_mfma_f32_16x16x32_bf16 v[76:79], v[170:173], v[210:213], v[76:79]
	v_mfma_f32_16x16x32_bf16 v[68:71], v[178:181], v[210:213], v[68:71]
	v_mfma_f32_16x16x32_bf16 v[124:127], v[174:177], v[190:193], v[124:127]
	v_mfma_f32_16x16x32_bf16 v[120:123], v[182:185], v[190:193], v[120:123]
	v_mfma_f32_16x16x32_bf16 v[108:111], v[174:177], v[198:201], v[108:111]
	v_mfma_f32_16x16x32_bf16 v[104:107], v[182:185], v[198:201], v[104:107]
	v_mfma_f32_16x16x32_bf16 v[92:95], v[174:177], v[206:209], v[92:95]
	v_mfma_f32_16x16x32_bf16 v[88:91], v[182:185], v[206:209], v[88:91]
	v_mfma_f32_16x16x32_bf16 v[76:79], v[174:177], v[214:217], v[76:79]
	v_mfma_f32_16x16x32_bf16 v[68:71], v[182:185], v[214:217], v[68:71]
	s_setprio 0
	s_barrier
	s_add_i32 s23, s23, s50
	s_mov_b32 m0, s23
	ds_read_b128 v[186:189], v156 offset:49152
	ds_read_b128 v[190:193], v156 offset:50176
	ds_read_b128 v[194:197], v156 offset:51200
	ds_read_b128 v[198:201], v156 offset:52224
	ds_read_b128 v[202:205], v156 offset:53248
	ds_read_b128 v[206:209], v156 offset:54272
	ds_read_b128 v[210:213], v156 offset:55296
	ds_read_b128 v[214:217], v156 offset:56320
	global_load_lds_dwordx4 v132, s[98:99]
	s_add_i32 m0, s23, 0x2000
	s_add_u32 s42, s42, 0x40080
	s_addc_u32 s43, s43, 0
	s_add_i32 s23, s33, s50
	global_load_lds_dwordx4 v136, s[98:99]
	s_mov_b32 m0, s23
	s_nop 0
	global_load_lds_dwordx4 v132, s[42:43]
	s_add_i32 m0, s23, 0x2000
	s_nop 0
	global_load_lds_dwordx4 v136, s[42:43]
	s_mov_b32 m0, s58
	s_nop 0
	global_load_lds_dwordx4 v130, s[100:101]
	s_mov_b32 m0, s59
	s_nop 0
	global_load_lds_dwordx4 v134, s[100:101]
	s_waitcnt vmcnt(8)
	s_waitcnt lgkmcnt(0)
	s_barrier
	s_setprio 1
	v_mfma_f32_16x16x32_bf16 v[56:59], v[146:149], v[186:189], v[56:59]
	v_mfma_f32_16x16x32_bf16 v[48:51], v[162:165], v[186:189], v[48:51]
	v_mfma_f32_16x16x32_bf16 v[40:43], v[146:149], v[194:197], v[40:43]
	v_mfma_f32_16x16x32_bf16 v[32:35], v[162:165], v[194:197], v[32:35]
	v_mfma_f32_16x16x32_bf16 v[24:27], v[146:149], v[202:205], v[24:27]
	v_mfma_f32_16x16x32_bf16 v[16:19], v[162:165], v[202:205], v[16:19]
	v_mfma_f32_16x16x32_bf16 v[8:11], v[146:149], v[210:213], v[8:11]
	v_mfma_f32_16x16x32_bf16 v[0:3], v[162:165], v[210:213], v[0:3]
	v_mfma_f32_16x16x32_bf16 v[56:59], v[158:161], v[190:193], v[56:59]
	v_mfma_f32_16x16x32_bf16 v[48:51], v[166:169], v[190:193], v[48:51]
	v_mfma_f32_16x16x32_bf16 v[40:43], v[158:161], v[198:201], v[40:43]
	v_mfma_f32_16x16x32_bf16 v[32:35], v[166:169], v[198:201], v[32:35]
	v_mfma_f32_16x16x32_bf16 v[24:27], v[158:161], v[206:209], v[24:27]
	v_mfma_f32_16x16x32_bf16 v[16:19], v[166:169], v[206:209], v[16:19]
	v_mfma_f32_16x16x32_bf16 v[8:11], v[158:161], v[214:217], v[8:11]
	v_mfma_f32_16x16x32_bf16 v[0:3], v[166:169], v[214:217], v[0:3]
	v_mfma_f32_16x16x32_bf16 v[60:63], v[170:173], v[186:189], v[60:63]
	v_mfma_f32_16x16x32_bf16 v[52:55], v[178:181], v[186:189], v[52:55]
	v_mfma_f32_16x16x32_bf16 v[44:47], v[170:173], v[194:197], v[44:47]
	v_mfma_f32_16x16x32_bf16 v[36:39], v[178:181], v[194:197], v[36:39]
	v_mfma_f32_16x16x32_bf16 v[28:31], v[170:173], v[202:205], v[28:31]
	v_mfma_f32_16x16x32_bf16 v[20:23], v[178:181], v[202:205], v[20:23]
	v_mfma_f32_16x16x32_bf16 v[12:15], v[170:173], v[210:213], v[12:15]
	v_mfma_f32_16x16x32_bf16 v[4:7], v[178:181], v[210:213], v[4:7]
	v_mfma_f32_16x16x32_bf16 v[60:63], v[174:177], v[190:193], v[60:63]
	v_mfma_f32_16x16x32_bf16 v[52:55], v[182:185], v[190:193], v[52:55]
	v_mfma_f32_16x16x32_bf16 v[44:47], v[174:177], v[198:201], v[44:47]
	v_mfma_f32_16x16x32_bf16 v[36:39], v[182:185], v[198:201], v[36:39]
	v_mfma_f32_16x16x32_bf16 v[28:31], v[174:177], v[206:209], v[28:31]
	v_mfma_f32_16x16x32_bf16 v[20:23], v[182:185], v[206:209], v[20:23]
	v_mfma_f32_16x16x32_bf16 v[12:15], v[174:177], v[214:217], v[12:15]
	v_mfma_f32_16x16x32_bf16 v[4:7], v[182:185], v[214:217], v[4:7]
	s_setprio 0
	s_barrier
	s_add_i32 s67, s67, 2
	s_add_u32 s40, s40, 0x100
	s_addc_u32 s41, s41, 0
	s_add_u32 s65, s65, 0x100
	s_addc_u32 s66, s66, 0
	s_cmp_gt_u32 s67, 13
	s_cbranch_scc0 .LBB0_1342
	s_and_b64 vcc, exec, s[14:15]
	s_cbranch_vccz .LBB0_1345
	s_barrier

.LBB0_1424:
	ds_read_b128 v[146:149], v156
	ds_read_b128 v[160:163], v156 offset:1024
	ds_read_b128 v[164:167], v156 offset:2048
	ds_read_b128 v[168:171], v156 offset:3072
	ds_read_b128 v[172:175], v157
	ds_read_b128 v[176:179], v157 offset:1024
	ds_read_b128 v[180:183], v157 offset:2048
	ds_read_b128 v[184:187], v157 offset:3072
	s_add_u32 s23, s38, 0xfff50080
	s_addc_u32 s33, s39, -1
	s_cmp_eq_u32 s65, 40
	s_cselect_b32 s43, s1, s33
	s_cselect_b32 s42, s0, s23
	s_cselect_b32 s41, s37, s64
	s_cselect_b32 s40, s36, s63
	s_add_i32 m0, s49, 0xc000
	ds_read_b128 v[188:191], v158
	ds_read_b128 v[192:195], v158 offset:1024
	ds_read_b128 v[196:199], v158 offset:2048
	ds_read_b128 v[200:203], v158 offset:3072
	ds_read_b128 v[204:207], v158 offset:4096
	ds_read_b128 v[208:211], v158 offset:5120
	ds_read_b128 v[212:215], v158 offset:6144
	ds_read_b128 v[216:219], v158 offset:7168
	global_load_lds_dwordx4 v138, s[38:39]
	s_add_i32 m0, s49, 0xe000
	s_nop 0
	global_load_lds_dwordx4 v140, s[38:39]
	s_waitcnt vmcnt(8)
	s_waitcnt lgkmcnt(0)
	s_barrier
	s_setprio 1
	v_mfma_f32_16x16x32_bf16 v[124:127], v[146:149], v[188:191], v[124:127]
	v_mfma_f32_16x16x32_bf16 v[120:123], v[164:167], v[188:191], v[120:123]
	v_mfma_f32_16x16x32_bf16 v[108:111], v[146:149], v[196:199], v[108:111]
	v_mfma_f32_16x16x32_bf16 v[104:107], v[164:167], v[196:199], v[104:107]
	v_mfma_f32_16x16x32_bf16 v[92:95], v[146:149], v[204:207], v[92:95]
	v_mfma_f32_16x16x32_bf16 v[88:91], v[164:167], v[204:207], v[88:91]
	v_mfma_f32_16x16x32_bf16 v[76:79], v[146:149], v[212:215], v[76:79]
	v_mfma_f32_16x16x32_bf16 v[72:75], v[164:167], v[212:215], v[72:75]
	v_mfma_f32_16x16x32_bf16 v[124:127], v[160:163], v[192:195], v[124:127]
	v_mfma_f32_16x16x32_bf16 v[120:123], v[168:171], v[192:195], v[120:123]
	v_mfma_f32_16x16x32_bf16 v[108:111], v[160:163], v[200:203], v[108:111]
	v_mfma_f32_16x16x32_bf16 v[104:107], v[168:171], v[200:203], v[104:107]
	v_mfma_f32_16x16x32_bf16 v[92:95], v[160:163], v[208:211], v[92:95]
	v_mfma_f32_16x16x32_bf16 v[88:91], v[168:171], v[208:211], v[88:91]
	v_mfma_f32_16x16x32_bf16 v[76:79], v[160:163], v[216:219], v[76:79]
	v_mfma_f32_16x16x32_bf16 v[72:75], v[168:171], v[216:219], v[72:75]
	v_mfma_f32_16x16x32_bf16 v[116:119], v[172:175], v[188:191], v[116:119]
	v_mfma_f32_16x16x32_bf16 v[112:115], v[180:183], v[188:191], v[112:115]
	v_mfma_f32_16x16x32_bf16 v[100:103], v[172:175], v[196:199], v[100:103]
	v_mfma_f32_16x16x32_bf16 v[96:99], v[180:183], v[196:199], v[96:99]
	v_mfma_f32_16x16x32_bf16 v[84:87], v[172:175], v[204:207], v[84:87]
	v_mfma_f32_16x16x32_bf16 v[80:83], v[180:183], v[204:207], v[80:83]
	v_mfma_f32_16x16x32_bf16 v[68:71], v[172:175], v[212:215], v[68:71]
	v_mfma_f32_16x16x32_bf16 v[64:67], v[180:183], v[212:215], v[64:67]
	v_mfma_f32_16x16x32_bf16 v[116:119], v[176:179], v[192:195], v[116:119]
	v_mfma_f32_16x16x32_bf16 v[112:115], v[184:187], v[192:195], v[112:115]
	v_mfma_f32_16x16x32_bf16 v[100:103], v[176:179], v[200:203], v[100:103]
	v_mfma_f32_16x16x32_bf16 v[96:99], v[184:187], v[200:203], v[96:99]
	v_mfma_f32_16x16x32_bf16 v[84:87], v[176:179], v[208:211], v[84:87]
	v_mfma_f32_16x16x32_bf16 v[80:83], v[184:187], v[208:211], v[80:83]
	v_mfma_f32_16x16x32_bf16 v[68:71], v[176:179], v[216:219], v[68:71]
	v_mfma_f32_16x16x32_bf16 v[64:67], v[184:187], v[216:219], v[64:67]
	s_setprio 0
	s_barrier
	s_add_u32 s98, s40, s16
	s_addc_u32 s99, s41, s17
	s_add_u32 s100, s42, s16
	s_addc_u32 s101, s43, s17
	s_add_i32 s23, s59, s48
	s_mov_b32 m0, s23
	ds_read_b128 v[188:191], v158 offset:16384
	ds_read_b128 v[192:195], v158 offset:17408
	ds_read_b128 v[196:199], v158 offset:18432
	ds_read_b128 v[200:203], v158 offset:19456
	ds_read_b128 v[204:207], v158 offset:20480
	ds_read_b128 v[208:211], v158 offset:21504
	ds_read_b128 v[212:215], v158 offset:22528
	ds_read_b128 v[216:219], v158 offset:23552
	global_load_lds_dwordx4 v132, s[40:41]
	s_add_i32 m0, s23, 0x2000
	s_add_u32 s66, s40, 0xb0000
	s_addc_u32 s67, s41, 0
	s_add_i32 s23, s60, s48
	global_load_lds_dwordx4 v136, s[40:41]
	s_mov_b32 m0, s23
	s_nop 0
	global_load_lds_dwordx4 v132, s[66:67]
	s_add_i32 m0, s23, 0x2000
	s_nop 0
	global_load_lds_dwordx4 v136, s[66:67]
	s_mov_b32 m0, s49
	s_nop 0
	global_load_lds_dwordx4 v130, s[42:43]
	s_mov_b32 m0, s50
	s_nop 0
	global_load_lds_dwordx4 v134, s[42:43]
	s_waitcnt vmcnt(8)
	s_waitcnt lgkmcnt(0)
	s_barrier
	s_setprio 1
	v_mfma_f32_16x16x32_bf16 v[60:63], v[146:149], v[188:191], v[60:63]
	v_mfma_f32_16x16x32_bf16 v[56:59], v[164:167], v[188:191], v[56:59]
	v_mfma_f32_16x16x32_bf16 v[44:47], v[146:149], v[196:199], v[44:47]
	v_mfma_f32_16x16x32_bf16 v[40:43], v[164:167], v[196:199], v[40:43]
	v_mfma_f32_16x16x32_bf16 v[28:31], v[146:149], v[204:207], v[28:31]
	v_mfma_f32_16x16x32_bf16 v[24:27], v[164:167], v[204:207], v[24:27]
	v_mfma_f32_16x16x32_bf16 v[12:15], v[146:149], v[212:215], v[12:15]
	v_mfma_f32_16x16x32_bf16 v[8:11], v[164:167], v[212:215], v[8:11]
	v_mfma_f32_16x16x32_bf16 v[60:63], v[160:163], v[192:195], v[60:63]
	v_mfma_f32_16x16x32_bf16 v[56:59], v[168:171], v[192:195], v[56:59]
	v_mfma_f32_16x16x32_bf16 v[44:47], v[160:163], v[200:203], v[44:47]
	v_mfma_f32_16x16x32_bf16 v[40:43], v[168:171], v[200:203], v[40:43]
	v_mfma_f32_16x16x32_bf16 v[28:31], v[160:163], v[208:211], v[28:31]
	v_mfma_f32_16x16x32_bf16 v[24:27], v[168:171], v[208:211], v[24:27]
	v_mfma_f32_16x16x32_bf16 v[12:15], v[160:163], v[216:219], v[12:15]
	v_mfma_f32_16x16x32_bf16 v[8:11], v[168:171], v[216:219], v[8:11]
	v_mfma_f32_16x16x32_bf16 v[52:55], v[172:175], v[188:191], v[52:55]
	v_mfma_f32_16x16x32_bf16 v[48:51], v[180:183], v[188:191], v[48:51]
	v_mfma_f32_16x16x32_bf16 v[36:39], v[172:175], v[196:199], v[36:39]
	v_mfma_f32_16x16x32_bf16 v[32:35], v[180:183], v[196:199], v[32:35]
	v_mfma_f32_16x16x32_bf16 v[20:23], v[172:175], v[204:207], v[20:23]
	v_mfma_f32_16x16x32_bf16 v[16:19], v[180:183], v[204:207], v[16:19]
	v_mfma_f32_16x16x32_bf16 v[4:7], v[172:175], v[212:215], v[4:7]
	v_mfma_f32_16x16x32_bf16 v[0:3], v[180:183], v[212:215], v[0:3]
	v_mfma_f32_16x16x32_bf16 v[52:55], v[176:179], v[192:195], v[52:55]
	v_mfma_f32_16x16x32_bf16 v[48:51], v[184:187], v[192:195], v[48:51]
	v_mfma_f32_16x16x32_bf16 v[36:39], v[176:179], v[200:203], v[36:39]
	v_mfma_f32_16x16x32_bf16 v[32:35], v[184:187], v[200:203], v[32:35]
	v_mfma_f32_16x16x32_bf16 v[20:23], v[176:179], v[208:211], v[20:23]
	v_mfma_f32_16x16x32_bf16 v[16:19], v[184:187], v[208:211], v[16:19]
	v_mfma_f32_16x16x32_bf16 v[4:7], v[176:179], v[216:219], v[4:7]
	v_mfma_f32_16x16x32_bf16 v[0:3], v[184:187], v[216:219], v[0:3]
	s_setprio 0
	s_barrier
	s_add_i32 s23, 0, 0x18000
	s_add_i32 s33, 0, 0x1c000
	v_add_u32_e32 v168, s23, v154
	v_add_u32_e32 v184, s33, v154
	ds_read_b128 v[146:149], v168
	ds_read_b128 v[160:163], v168 offset:1024
	ds_read_b128 v[164:167], v168 offset:2048
	ds_read_b128 v[168:171], v168 offset:3072
	ds_read_b128 v[172:175], v184
	ds_read_b128 v[176:179], v184 offset:1024
	ds_read_b128 v[180:183], v184 offset:2048
	ds_read_b128 v[184:187], v184 offset:3072
	s_add_u32 s42, s42, 0xb0000
	s_addc_u32 s43, s43, 0
	s_mov_b32 m0, s51
	ds_read_b128 v[188:191], v158 offset:32768
	ds_read_b128 v[192:195], v158 offset:33792
	ds_read_b128 v[196:199], v158 offset:34816
	ds_read_b128 v[200:203], v158 offset:35840
	ds_read_b128 v[204:207], v158 offset:36864
	ds_read_b128 v[208:211], v158 offset:37888
	ds_read_b128 v[212:215], v158 offset:38912
	ds_read_b128 v[216:219], v158 offset:39936
	global_load_lds_dwordx4 v130, s[42:43]
	s_mov_b32 m0, s52
	s_nop 0
	global_load_lds_dwordx4 v134, s[42:43]
	s_waitcnt vmcnt(8)
	s_waitcnt lgkmcnt(0)
	s_barrier
	s_setprio 1
	v_mfma_f32_16x16x32_bf16 v[124:127], v[146:149], v[188:191], v[124:127]
	v_mfma_f32_16x16x32_bf16 v[120:123], v[164:167], v[188:191], v[120:123]
	v_mfma_f32_16x16x32_bf16 v[108:111], v[146:149], v[196:199], v[108:111]
	v_mfma_f32_16x16x32_bf16 v[104:107], v[164:167], v[196:199], v[104:107]
	v_mfma_f32_16x16x32_bf16 v[92:95], v[146:149], v[204:207], v[92:95]
	v_mfma_f32_16x16x32_bf16 v[88:91], v[164:167], v[204:207], v[88:91]
	v_mfma_f32_16x16x32_bf16 v[76:79], v[146:149], v[212:215], v[76:79]
	v_mfma_f32_16x16x32_bf16 v[72:75], v[164:167], v[212:215], v[72:75]
	v_mfma_f32_16x16x32_bf16 v[124:127], v[160:163], v[192:195], v[124:127]
	v_mfma_f32_16x16x32_bf16 v[120:123], v[168:171], v[192:195], v[120:123]
	v_mfma_f32_16x16x32_bf16 v[108:111], v[160:163], v[200:203], v[108:111]
	v_mfma_f32_16x16x32_bf16 v[104:107], v[168:171], v[200:203], v[104:107]
	v_mfma_f32_16x16x32_bf16 v[92:95], v[160:163], v[208:211], v[92:95]
	v_mfma_f32_16x16x32_bf16 v[88:91], v[168:171], v[208:211], v[88:91]
	v_mfma_f32_16x16x32_bf16 v[76:79], v[160:163], v[216:219], v[76:79]
	v_mfma_f32_16x16x32_bf16 v[72:75], v[168:171], v[216:219], v[72:75]
	v_mfma_f32_16x16x32_bf16 v[116:119], v[172:175], v[188:191], v[116:119]
	v_mfma_f32_16x16x32_bf16 v[112:115], v[180:183], v[188:191], v[112:115]
	v_mfma_f32_16x16x32_bf16 v[100:103], v[172:175], v[196:199], v[100:103]
	v_mfma_f32_16x16x32_bf16 v[96:99], v[180:183], v[196:199], v[96:99]
	v_mfma_f32_16x16x32_bf16 v[84:87], v[172:175], v[204:207], v[84:87]
	v_mfma_f32_16x16x32_bf16 v[80:83], v[180:183], v[204:207], v[80:83]
	v_mfma_f32_16x16x32_bf16 v[68:71], v[172:175], v[212:215], v[68:71]
	v_mfma_f32_16x16x32_bf16 v[64:67], v[180:183], v[212:215], v[64:67]
	v_mfma_f32_16x16x32_bf16 v[116:119], v[176:179], v[192:195], v[116:119]
	v_mfma_f32_16x16x32_bf16 v[112:115], v[184:187], v[192:195], v[112:115]
	v_mfma_f32_16x16x32_bf16 v[100:103], v[176:179], v[200:203], v[100:103]
	v_mfma_f32_16x16x32_bf16 v[96:99], v[184:187], v[200:203], v[96:99]
	v_mfma_f32_16x16x32_bf16 v[84:87], v[176:179], v[208:211], v[84:87]
	v_mfma_f32_16x16x32_bf16 v[80:83], v[184:187], v[208:211], v[80:83]
	v_mfma_f32_16x16x32_bf16 v[68:71], v[176:179], v[216:219], v[68:71]
	v_mfma_f32_16x16x32_bf16 v[64:67], v[184:187], v[216:219], v[64:67]
	s_setprio 0
	s_barrier
	s_add_i32 s23, s23, s48
	s_mov_b32 m0, s23
	ds_read_b128 v[188:191], v158 offset:49152
	ds_read_b128 v[192:195], v158 offset:50176
	ds_read_b128 v[196:199], v158 offset:51200
	ds_read_b128 v[200:203], v158 offset:52224
	ds_read_b128 v[204:207], v158 offset:53248
	ds_read_b128 v[208:211], v158 offset:54272
	ds_read_b128 v[212:215], v158 offset:55296
	ds_read_b128 v[216:219], v158 offset:56320
	global_load_lds_dwordx4 v132, s[98:99]
	s_add_i32 m0, s23, 0x2000
	s_add_u32 s40, s40, 0xb0080
	s_addc_u32 s41, s41, 0
	s_add_i32 s23, s33, s48
	global_load_lds_dwordx4 v136, s[98:99]
	s_mov_b32 m0, s23
	s_nop 0
	global_load_lds_dwordx4 v132, s[40:41]
	s_add_i32 m0, s23, 0x2000
	s_nop 0
	global_load_lds_dwordx4 v136, s[40:41]
	s_mov_b32 m0, s56
	s_nop 0
	global_load_lds_dwordx4 v130, s[100:101]
	s_mov_b32 m0, s57
	s_nop 0
	global_load_lds_dwordx4 v134, s[100:101]
	s_waitcnt vmcnt(8)
	s_waitcnt lgkmcnt(0)
	s_barrier
	s_setprio 1
	v_mfma_f32_16x16x32_bf16 v[60:63], v[146:149], v[188:191], v[60:63]
	v_mfma_f32_16x16x32_bf16 v[56:59], v[164:167], v[188:191], v[56:59]
	v_mfma_f32_16x16x32_bf16 v[44:47], v[146:149], v[196:199], v[44:47]
	v_mfma_f32_16x16x32_bf16 v[40:43], v[164:167], v[196:199], v[40:43]
	v_mfma_f32_16x16x32_bf16 v[28:31], v[146:149], v[204:207], v[28:31]
	v_mfma_f32_16x16x32_bf16 v[24:27], v[164:167], v[204:207], v[24:27]
	v_mfma_f32_16x16x32_bf16 v[12:15], v[146:149], v[212:215], v[12:15]
	v_mfma_f32_16x16x32_bf16 v[8:11], v[164:167], v[212:215], v[8:11]
	v_mfma_f32_16x16x32_bf16 v[60:63], v[160:163], v[192:195], v[60:63]
	v_mfma_f32_16x16x32_bf16 v[56:59], v[168:171], v[192:195], v[56:59]
	v_mfma_f32_16x16x32_bf16 v[44:47], v[160:163], v[200:203], v[44:47]
	v_mfma_f32_16x16x32_bf16 v[40:43], v[168:171], v[200:203], v[40:43]
	v_mfma_f32_16x16x32_bf16 v[28:31], v[160:163], v[208:211], v[28:31]
	v_mfma_f32_16x16x32_bf16 v[24:27], v[168:171], v[208:211], v[24:27]
	v_mfma_f32_16x16x32_bf16 v[12:15], v[160:163], v[216:219], v[12:15]
	v_mfma_f32_16x16x32_bf16 v[8:11], v[168:171], v[216:219], v[8:11]
	v_mfma_f32_16x16x32_bf16 v[52:55], v[172:175], v[188:191], v[52:55]
	v_mfma_f32_16x16x32_bf16 v[48:51], v[180:183], v[188:191], v[48:51]
	v_mfma_f32_16x16x32_bf16 v[36:39], v[172:175], v[196:199], v[36:39]
	v_mfma_f32_16x16x32_bf16 v[32:35], v[180:183], v[196:199], v[32:35]
	v_mfma_f32_16x16x32_bf16 v[20:23], v[172:175], v[204:207], v[20:23]
	v_mfma_f32_16x16x32_bf16 v[16:19], v[180:183], v[204:207], v[16:19]
	v_mfma_f32_16x16x32_bf16 v[4:7], v[172:175], v[212:215], v[4:7]
	v_mfma_f32_16x16x32_bf16 v[0:3], v[180:183], v[212:215], v[0:3]
	v_mfma_f32_16x16x32_bf16 v[52:55], v[176:179], v[192:195], v[52:55]
	v_mfma_f32_16x16x32_bf16 v[48:51], v[184:187], v[192:195], v[48:51]
	v_mfma_f32_16x16x32_bf16 v[36:39], v[176:179], v[200:203], v[36:39]
	v_mfma_f32_16x16x32_bf16 v[32:35], v[184:187], v[200:203], v[32:35]
	v_mfma_f32_16x16x32_bf16 v[20:23], v[176:179], v[208:211], v[20:23]
	v_mfma_f32_16x16x32_bf16 v[16:19], v[184:187], v[208:211], v[16:19]
	v_mfma_f32_16x16x32_bf16 v[4:7], v[176:179], v[216:219], v[4:7]
	v_mfma_f32_16x16x32_bf16 v[0:3], v[184:187], v[216:219], v[0:3]
	s_setprio 0
	s_barrier
	s_add_i32 s65, s65, 2
	s_add_u32 s38, s38, 0x100
	s_addc_u32 s39, s39, 0
	s_add_u32 s63, s63, 0x100
	s_addc_u32 s64, s64, 0
	s_cmp_gt_u32 s65, 41
	s_cbranch_scc0 .LBB0_1424
	s_and_b64 vcc, exec, s[18:19]
	s_cbranch_vccz .LBB0_1427
	s_barrier

	.amdhsa_kernel _Z14fwd_megakernel6Params
		.amdhsa_group_segment_fixed_size 0
		.amdhsa_private_segment_fixed_size 0
		.amdhsa_kernarg_size 512
		.amdhsa_user_sgpr_count 2
		.amdhsa_user_sgpr_dispatch_ptr 0
		.amdhsa_user_sgpr_queue_ptr 0
		.amdhsa_user_sgpr_kernarg_segment_ptr 1
		.amdhsa_user_sgpr_dispatch_id 0
		.amdhsa_user_sgpr_kernarg_preload_length 0
		.amdhsa_user_sgpr_kernarg_preload_offset 0
		.amdhsa_user_sgpr_private_segment_size 0
		.amdhsa_uses_dynamic_stack 0
		.amdhsa_enable_private_segment 0
		.amdhsa_system_sgpr_workgroup_id_x 1
		.amdhsa_system_sgpr_workgroup_id_y 0
		.amdhsa_system_sgpr_workgroup_id_z 0
		.amdhsa_system_sgpr_workgroup_info 0
		.amdhsa_system_vgpr_workitem_id 2
		.amdhsa_next_free_vgpr 256
		.amdhsa_next_free_sgpr 102
		.amdhsa_accum_offset 256
		.amdhsa_reserve_vcc 1
		.amdhsa_float_round_mode_32 0
		.amdhsa_float_round_mode_16_64 0
		.amdhsa_float_denorm_mode_32 3
		.amdhsa_float_denorm_mode_16_64 3
		.amdhsa_dx10_clamp 1
		.amdhsa_ieee_mode 1
		.amdhsa_fp16_overflow 0
		.amdhsa_tg_split 0
		.amdhsa_exception_fp_ieee_invalid_op 0
		.amdhsa_exception_fp_denorm_src 0
		.amdhsa_exception_fp_ieee_div_zero 0
		.amdhsa_exception_fp_ieee_overflow 0
		.amdhsa_exception_fp_ieee_underflow 0
		.amdhsa_exception_fp_ieee_inexact 0
		.amdhsa_exception_int_div_zero 0
	.end_amdhsa_kernel

amdhsa.kernels:
  - .agpr_count:     0
    .args:
      - .offset:         0
        .size:           256
        .value_kind:     by_value
      - .offset:         256
        .size:           4
        .value_kind:     hidden_block_count_x
      - .offset:         260
        .size:           4
        .value_kind:     hidden_block_count_y
      - .offset:         264
        .size:           4
        .value_kind:     hidden_block_count_z
      - .offset:         268
        .size:           2
        .value_kind:     hidden_group_size_x
      - .offset:         270
        .size:           2
        .value_kind:     hidden_group_size_y
      - .offset:         272
        .size:           2
        .value_kind:     hidden_group_size_z
      - .offset:         274
        .size:           2
        .value_kind:     hidden_remainder_x
      - .offset:         276
        .size:           2
        .value_kind:     hidden_remainder_y
      - .offset:         278
        .size:           2
        .value_kind:     hidden_remainder_z
      - .offset:         296
        .size:           8
        .value_kind:     hidden_global_offset_x
      - .offset:         304
        .size:           8
        .value_kind:     hidden_global_offset_y
      - .offset:         312
        .size:           8
        .value_kind:     hidden_global_offset_z
      - .offset:         320
        .size:           2
        .value_kind:     hidden_grid_dims
      - .offset:         344
        .size:           8
        .value_kind:     hidden_multigrid_sync_arg
      - .offset:         376
        .size:           4
        .value_kind:     hidden_dynamic_lds_size
    .group_segment_fixed_size: 0
    .kernarg_segment_align: 8
    .kernarg_segment_size: 512
    .language:       OpenCL C
    .language_version:
      - 2
      - 0
    .max_flat_workgroup_size: 512
    .name:           _Z14fwd_megakernel6Params
    .private_segment_fixed_size: 0
    .sgpr_count:     108
    .sgpr_spill_count: 44
    .symbol:         _Z14fwd_megakernel6Params.kd
    .uniform_work_group_size: 1
    .uses_dynamic_stack: false
    .vgpr_count:     256
    .vgpr_spill_count: 0
    .wavefront_size: 64
